# K-loop edge: loop-control and pointer-select SALU moved from the head of the SP1 load segment into the MFMA shadow of the previous compute segment (asm guide 7.11)
# speedup vs baseline: 1.0095x; 1.0095x over previous
; template <class Epi, class Sched, bool ALIGN_EPI = false, bool SP2 = false, bool KSEG = false>
; __device__ __forceinline__ void gemm_phase(PG8_LAS unsigned char* lds, const Gemm g, const Sched& S, const Epi& E) {
;     ...
;         const char* nA = has_next ? (const char*)g.A + (size_t)nxt.pm * tstep : cA; const char* nB = has_next ? (const char*)g.Bt + (size_t)nxt.pn * tstep : cB;
;         for (int t = 0; t < nt; t += 2) {
;             const bool last = (t == nt - 2);
;             const char* a1 = cA + (size_t)(t + 1) * kstep;
;             const char* a2 = last ? nA : cA + (size_t)(t + 2) * kstep; const char* b2 = last ? nB : cB + (size_t)(t + 2) * kstep;
;             const char* a3 = a2 + kstep; const char* b3 = b2 + kstep;
;             if (last && has_next) S.a_ready(nxt);
;     ...
; #pragma unroll
;         for (int a = 0; a < 2; ++a)
; #pragma unroll
;             for (int b = 0; b < 2; ++b)
; #pragma unroll
;                 for (int m = 0; m < 4; ++m)
; #pragma unroll
;                     for (int n = 0; n < 2; ++n) acc[a][b][m][n] = (f32x4){0.f, 0.f, 0.f, 0.f};
;         cur = nxt; cA = nA; cB = nB; ++ui;
.LBB0_119:
	s_ashr_i32 s21, s20, 31
	s_lshl_b64 s[22:23], s[20:21], 20
	s_add_u32 s22, s74, s22
	s_addc_u32 s23, s75, s23
	s_and_b64 s[24:25], s[2:3], exec
	s_cselect_b32 s21, s23, s29
	s_cselect_b32 s64, s22, s28
	s_ashr_i32 s19, s18, 31
	s_lshl_b64 s[24:25], s[18:19], 20
	s_add_u32 s24, s8, s24
	s_addc_u32 s25, s9, s25
	s_and_b64 s[42:43], s[2:3], exec
	s_cselect_b32 s19, s25, s31
	s_cselect_b32 s65, s24, s30
	s_add_u32 s28, s28, 0x80080
	s_addc_u32 s29, s29, 0
	s_add_u32 s66, s30, 0x100
	v_mov_b32_e32 v2, 0
	s_addc_u32 s67, s31, 0
	s_mov_b32 s80, -2
	v_mov_b32_e32 v3, v2
	v_mov_b32_e32 v4, v2
	v_mov_b32_e32 v5, v2
	v_mov_b32_e32 v6, v2
	v_mov_b32_e32 v7, v2
	v_mov_b32_e32 v8, v2
	v_mov_b32_e32 v9, v2
	s_waitcnt vmcnt(0)
	v_mov_b32_e32 v18, v2
	v_mov_b32_e32 v19, v2
	v_mov_b32_e32 v20, v2
	v_mov_b32_e32 v21, v2
	v_mov_b32_e32 v22, v2
	v_mov_b32_e32 v23, v2
	v_mov_b32_e32 v24, v2
	v_mov_b32_e32 v25, v2
	v_mov_b32_e32 v34, v2
	v_mov_b32_e32 v35, v2
	v_mov_b32_e32 v36, v2
	v_mov_b32_e32 v37, v2
	v_mov_b32_e32 v38, v2
	s_waitcnt lgkmcnt(0)
	v_mov_b32_e32 v39, v2
	v_mov_b32_e32 v40, v2
	v_mov_b32_e32 v41, v2
	v_mov_b32_e32 v50, v2
	v_mov_b32_e32 v51, v2
	v_mov_b32_e32 v52, v2
	v_mov_b32_e32 v53, v2
	v_mov_b32_e32 v54, v2
	v_mov_b32_e32 v55, v2
	v_mov_b32_e32 v56, v2
	v_mov_b32_e32 v57, v2
	v_mov_b32_e32 v10, v2
	v_mov_b32_e32 v11, v2
	v_mov_b32_e32 v12, v2
	v_mov_b32_e32 v13, v2
	v_mov_b32_e32 v14, v2
	v_mov_b32_e32 v15, v2
	v_mov_b32_e32 v16, v2
	v_mov_b32_e32 v17, v2
	v_mov_b32_e32 v26, v2
	v_mov_b32_e32 v27, v2
	v_mov_b32_e32 v28, v2
	v_mov_b32_e32 v29, v2
	v_mov_b32_e32 v30, v2
	v_mov_b32_e32 v31, v2
	v_mov_b32_e32 v32, v2
	v_mov_b32_e32 v33, v2
	v_mov_b32_e32 v42, v2
	v_mov_b32_e32 v43, v2
	v_mov_b32_e32 v44, v2
	v_mov_b32_e32 v45, v2
	v_mov_b32_e32 v46, v2
	v_mov_b32_e32 v47, v2
	v_mov_b32_e32 v48, v2
	v_mov_b32_e32 v49, v2
	v_mov_b32_e32 v58, v2
	v_mov_b32_e32 v59, v2
	v_mov_b32_e32 v60, v2
	v_mov_b32_e32 v61, v2
	v_mov_b32_e32 v62, v2
	v_mov_b32_e32 v63, v2
	v_mov_b32_e32 v64, v2
	v_mov_b32_e32 v65, v2
	v_mov_b32_e32 v66, v2
	v_mov_b32_e32 v67, v2
	v_mov_b32_e32 v68, v2
	v_mov_b32_e32 v69, v2
	v_mov_b32_e32 v70, v2
	v_mov_b32_e32 v71, v2
	v_mov_b32_e32 v72, v2
	v_mov_b32_e32 v73, v2
	v_mov_b32_e32 v82, v2
	v_mov_b32_e32 v83, v2
	v_mov_b32_e32 v84, v2
	v_mov_b32_e32 v85, v2
	v_mov_b32_e32 v86, v2
	v_mov_b32_e32 v87, v2
	v_mov_b32_e32 v88, v2
	v_mov_b32_e32 v89, v2
	v_mov_b32_e32 v98, v2
	v_mov_b32_e32 v99, v2
	v_mov_b32_e32 v100, v2
	v_mov_b32_e32 v101, v2
	v_mov_b32_e32 v102, v2
	v_mov_b32_e32 v103, v2
	v_mov_b32_e32 v104, v2
	v_mov_b32_e32 v105, v2
	v_mov_b32_e32 v114, v2
	v_mov_b32_e32 v115, v2
	v_mov_b32_e32 v116, v2
	v_mov_b32_e32 v117, v2
	v_mov_b32_e32 v118, v2
	v_mov_b32_e32 v119, v2
	v_mov_b32_e32 v120, v2
	v_mov_b32_e32 v121, v2
	v_mov_b32_e32 v74, v2
	v_mov_b32_e32 v75, v2
	v_mov_b32_e32 v76, v2
	v_mov_b32_e32 v77, v2
	v_mov_b32_e32 v78, v2
	v_mov_b32_e32 v79, v2
	v_mov_b32_e32 v80, v2
	v_mov_b32_e32 v81, v2
	v_mov_b32_e32 v90, v2
	v_mov_b32_e32 v91, v2
	v_mov_b32_e32 v92, v2
	v_mov_b32_e32 v93, v2
	v_mov_b32_e32 v94, v2
	v_mov_b32_e32 v95, v2
	v_mov_b32_e32 v96, v2
	v_mov_b32_e32 v97, v2
	v_mov_b32_e32 v106, v2
	v_mov_b32_e32 v107, v2
	v_mov_b32_e32 v108, v2
	v_mov_b32_e32 v109, v2
	v_mov_b32_e32 v110, v2
	v_mov_b32_e32 v111, v2
	v_mov_b32_e32 v112, v2
	v_mov_b32_e32 v113, v2
	v_mov_b32_e32 v122, v2
	v_mov_b32_e32 v123, v2
	v_mov_b32_e32 v124, v2
	v_mov_b32_e32 v125, v2
	v_mov_b32_e32 v126, v2
	v_mov_b32_e32 v127, v2
	v_mov_b32_e32 v128, v2
	v_mov_b32_e32 v129, v2
	s_add_u32 s30, s28, 0xfff80080
	s_addc_u32 s31, s29, -1
	s_cmp_eq_u32 s80, 28
	s_cselect_b32 s43, s21, s31
	s_cselect_b32 s42, s64, s30
	s_cselect_b32 s31, s19, s67
	s_cselect_b32 s30, s65, s66
	s_add_u32 s98, s28, 0xfff80000
	s_addc_u32 s99, s29, -1
.LBB0_120:
	ds_read_b128 v[146:149], v156
	ds_read_b128 v[150:153], v156 offset:1024
	ds_read_b128 v[160:163], v156 offset:2048
	ds_read_b128 v[164:167], v156 offset:3072
	ds_read_b128 v[168:171], v157
	ds_read_b128 v[172:175], v157 offset:1024
	ds_read_b128 v[176:179], v157 offset:2048
	ds_read_b128 v[180:183], v157 offset:3072
	s_mov_b32 m0, s51
	v_lshl_add_u64 v[216:217], s[98:99], 0, v[136:137]
	global_load_lds_dwordx4 v[216:217], off
	s_mov_b32 m0, s58
	v_lshl_add_u64 v[216:217], s[98:99], 0, v[132:133]
	global_load_lds_dwordx4 v[216:217], off
	v_lshl_add_u64 v[216:217], s[28:29], 0, v[138:139]
	s_add_i32 m0, s27, 0xc000
	ds_read_b128 v[184:187], v158
	ds_read_b128 v[188:191], v158 offset:1024
	ds_read_b128 v[192:195], v158 offset:2048
	ds_read_b128 v[196:199], v158 offset:3072
	ds_read_b128 v[200:203], v158 offset:4096
	ds_read_b128 v[204:207], v158 offset:5120
	ds_read_b128 v[208:211], v158 offset:6144
	ds_read_b128 v[212:215], v158 offset:7168
	global_load_lds_dwordx4 v[216:217], off
	s_add_i32 m0, s27, 0xe000
	v_lshl_add_u64 v[216:217], s[28:29], 0, v[140:141]
	global_load_lds_dwordx4 v[216:217], off
	s_waitcnt vmcnt(8) lgkmcnt(0)
	s_barrier
; #define PG8_STAGE(bufoff, gbase, voff) do { _Pragma("unroll") for (int _i = 0; _i < 2; ++_i) \
;         __builtin_amdgcn_global_load_lds((const unsigned*)((const char*)(gbase) + (voff)[_i]), (PG8_LAS unsigned*)(lds + (bufoff) + ldsw + _i * 8192), 16, 0, 0); } while (0)
; #define PG8_LDA(dst, b, h) do { _Pragma("unroll") for (int m = 0; m < 4; ++m) _Pragma("unroll") for (int k = 0; k < 2; ++k) dst[m][k] = *(const PG8_LAS bf16x8*)(lds + PG8_SA(b, h) + aoff + m * 2048 + k * 1024); } while (0)
; #define PG8_LDB(dst, b, h) do { _Pragma("unroll") for (int n = 0; n < 2; ++n) _Pragma("unroll") for (int k = 0; k < 2; ++k) dst[n][k] = *(const PG8_LAS bf16x8*)(lds + PG8_SB(b, h) + boff + n * 2048 + k * 1024); } while (0)
; #define PG8_MMA(ai, bj, At, Bt) do { __builtin_amdgcn_s_setprio(1); _Pragma("unroll") for (int m = 0; m < 4; ++m) _Pragma("unroll") for (int n = 0; n < 2; ++n) _Pragma("unroll") for (int k = 0; k < 2; ++k) \
;         acc[ai][bj][m][n] = __builtin_amdgcn_mfma_f32_16x16x32_bf16(Bt[n][k], At[m][k], acc[ai][bj][m][n], 0, 0, 0); __builtin_amdgcn_s_setprio(0); } while (0)
; #define PG8_WAIT_V(n) asm volatile("s_waitcnt vmcnt(" #n ")" ::: "memory")
; #define PG8_WAIT_L(n) asm volatile("s_waitcnt lgkmcnt(" #n ")" ::: "memory")
; #define PG8_BAR __builtin_amdgcn_s_barrier()
; #define PG8_SCHED __builtin_amdgcn_sched_barrier(0)
; template <class Epi, class Sched, bool ALIGN_EPI = false, bool SP2 = false, bool KSEG = false>
; __device__ __forceinline__ void gemm_phase(PG8_LAS unsigned char* lds, const Gemm g, const Sched& S, const Epi& E) {
;     ...
;             PG8_LDB(B0, 0, 0); PG8_LDB(B1, 0, 1); PG8_SCHED; PG8_LDA(At, 0, 0); PG8_STAGE(PG8_SA(1, 1), a1 + hstep, voffA);
;             PG8_WAIT_V(8); PG8_WAIT_L(0); PG8_BAR; PG8_MMA(0, 0, At, B0); PG8_MMA(0, 1, At, B1); PG8_BAR; PG8_SCHED;
;             PG8_LDA(At, 0, 1); PG8_STAGE(PG8_SB(0, 0), b2, voffB); PG8_STAGE(PG8_SB(0, 1), b2 + hstep, voffB); PG8_STAGE(PG8_SA(0, 0), a2, voffA);
;             PG8_WAIT_V(8); PG8_WAIT_L(0); PG8_BAR; PG8_MMA(1, 0, At, B0); PG8_MMA(1, 1, At, B1); PG8_BAR; PG8_SCHED;
	s_setprio 1
	v_mfma_f32_16x16x32_bf16 v[126:129], v[146:149], v[184:187], v[126:129]
	v_mfma_f32_16x16x32_bf16 v[122:125], v[160:163], v[184:187], v[122:125]
	v_mfma_f32_16x16x32_bf16 v[110:113], v[146:149], v[192:195], v[110:113]
	v_mfma_f32_16x16x32_bf16 v[106:109], v[160:163], v[192:195], v[106:109]
	v_mfma_f32_16x16x32_bf16 v[94:97], v[146:149], v[200:203], v[94:97]
	v_mfma_f32_16x16x32_bf16 v[90:93], v[160:163], v[200:203], v[90:93]
	v_mfma_f32_16x16x32_bf16 v[78:81], v[146:149], v[208:211], v[78:81]
	v_mfma_f32_16x16x32_bf16 v[74:77], v[160:163], v[208:211], v[74:77]
	v_mfma_f32_16x16x32_bf16 v[126:129], v[150:153], v[188:191], v[126:129]
	v_mfma_f32_16x16x32_bf16 v[122:125], v[164:167], v[188:191], v[122:125]
	v_mfma_f32_16x16x32_bf16 v[110:113], v[150:153], v[196:199], v[110:113]
	v_mfma_f32_16x16x32_bf16 v[106:109], v[164:167], v[196:199], v[106:109]
	v_mfma_f32_16x16x32_bf16 v[94:97], v[150:153], v[204:207], v[94:97]
	v_mfma_f32_16x16x32_bf16 v[90:93], v[164:167], v[204:207], v[90:93]
	v_mfma_f32_16x16x32_bf16 v[78:81], v[150:153], v[212:215], v[78:81]
	v_mfma_f32_16x16x32_bf16 v[74:77], v[164:167], v[212:215], v[74:77]
	s_setprio 0
	s_setprio 1
	v_mfma_f32_16x16x32_bf16 v[118:121], v[168:171], v[184:187], v[118:121]
	v_mfma_f32_16x16x32_bf16 v[114:117], v[176:179], v[184:187], v[114:117]
	v_mfma_f32_16x16x32_bf16 v[102:105], v[168:171], v[192:195], v[102:105]
	v_mfma_f32_16x16x32_bf16 v[98:101], v[176:179], v[192:195], v[98:101]
	v_mfma_f32_16x16x32_bf16 v[86:89], v[168:171], v[200:203], v[86:89]
	v_mfma_f32_16x16x32_bf16 v[82:85], v[176:179], v[200:203], v[82:85]
	v_mfma_f32_16x16x32_bf16 v[70:73], v[168:171], v[208:211], v[70:73]
	v_mfma_f32_16x16x32_bf16 v[66:69], v[176:179], v[208:211], v[66:69]
	v_mfma_f32_16x16x32_bf16 v[118:121], v[172:175], v[188:191], v[118:121]
	v_mfma_f32_16x16x32_bf16 v[114:117], v[180:183], v[188:191], v[114:117]
	v_mfma_f32_16x16x32_bf16 v[102:105], v[172:175], v[196:199], v[102:105]
	v_mfma_f32_16x16x32_bf16 v[98:101], v[180:183], v[196:199], v[98:101]
	v_mfma_f32_16x16x32_bf16 v[86:89], v[172:175], v[204:207], v[86:89]
	v_mfma_f32_16x16x32_bf16 v[82:85], v[180:183], v[204:207], v[82:85]
	v_mfma_f32_16x16x32_bf16 v[70:73], v[172:175], v[212:215], v[70:73]
	v_mfma_f32_16x16x32_bf16 v[66:69], v[180:183], v[212:215], v[66:69]
	s_setprio 0
	s_barrier
	s_add_i32 s33, s60, s44
	v_lshl_add_u64 v[216:217], s[30:31], 0, v[134:135]
	s_mov_b32 m0, s33
	ds_read_b128 v[184:187], v158 offset:16384
	ds_read_b128 v[188:191], v158 offset:17408
	ds_read_b128 v[192:195], v158 offset:18432
	ds_read_b128 v[196:199], v158 offset:19456
	ds_read_b128 v[200:203], v158 offset:20480
	ds_read_b128 v[204:207], v158 offset:21504
	ds_read_b128 v[208:211], v158 offset:22528
	ds_read_b128 v[212:215], v158 offset:23552
	global_load_lds_dwordx4 v[216:217], off
	s_add_i32 m0, s33, 0x2000
	s_add_u32 s84, s30, 0x80000
	v_lshl_add_u64 v[218:219], s[30:31], 0, v[130:131]
	s_addc_u32 s85, s31, 0
	s_add_i32 s33, s61, s44
	global_load_lds_dwordx4 v[218:219], off
	s_mov_b32 m0, s33
	v_lshl_add_u64 v[220:221], s[84:85], 0, v[134:135]
	global_load_lds_dwordx4 v[220:221], off
	s_add_i32 m0, s33, 0x2000
	v_lshl_add_u64 v[220:221], s[84:85], 0, v[130:131]
	global_load_lds_dwordx4 v[220:221], off
	s_waitcnt vmcnt(6) lgkmcnt(0)
	s_barrier
	s_setprio 1
	v_mfma_f32_16x16x32_bf16 v[62:65], v[146:149], v[184:187], v[62:65]
	v_mfma_f32_16x16x32_bf16 v[58:61], v[160:163], v[184:187], v[58:61]
	v_mfma_f32_16x16x32_bf16 v[46:49], v[146:149], v[192:195], v[46:49]
	v_mfma_f32_16x16x32_bf16 v[42:45], v[160:163], v[192:195], v[42:45]
	v_mfma_f32_16x16x32_bf16 v[30:33], v[146:149], v[200:203], v[30:33]
	v_mfma_f32_16x16x32_bf16 v[26:29], v[160:163], v[200:203], v[26:29]
	v_mfma_f32_16x16x32_bf16 v[14:17], v[146:149], v[208:211], v[14:17]
	v_mfma_f32_16x16x32_bf16 v[10:13], v[160:163], v[208:211], v[10:13]
	v_mfma_f32_16x16x32_bf16 v[62:65], v[150:153], v[188:191], v[62:65]
	v_mfma_f32_16x16x32_bf16 v[58:61], v[164:167], v[188:191], v[58:61]
	v_mfma_f32_16x16x32_bf16 v[46:49], v[150:153], v[196:199], v[46:49]
	v_mfma_f32_16x16x32_bf16 v[42:45], v[164:167], v[196:199], v[42:45]
	v_mfma_f32_16x16x32_bf16 v[30:33], v[150:153], v[204:207], v[30:33]
	v_mfma_f32_16x16x32_bf16 v[26:29], v[164:167], v[204:207], v[26:29]
	v_mfma_f32_16x16x32_bf16 v[14:17], v[150:153], v[212:215], v[14:17]
	v_mfma_f32_16x16x32_bf16 v[10:13], v[164:167], v[212:215], v[10:13]
	s_setprio 0
	s_setprio 1
	v_mfma_f32_16x16x32_bf16 v[54:57], v[168:171], v[184:187], v[54:57]
	v_mfma_f32_16x16x32_bf16 v[50:53], v[176:179], v[184:187], v[50:53]
	v_mfma_f32_16x16x32_bf16 v[38:41], v[168:171], v[192:195], v[38:41]
	v_mfma_f32_16x16x32_bf16 v[34:37], v[176:179], v[192:195], v[34:37]
	v_mfma_f32_16x16x32_bf16 v[22:25], v[168:171], v[200:203], v[22:25]
	v_mfma_f32_16x16x32_bf16 v[18:21], v[176:179], v[200:203], v[18:21]
	v_mfma_f32_16x16x32_bf16 v[6:9], v[168:171], v[208:211], v[6:9]
	v_mfma_f32_16x16x32_bf16 v[2:5], v[176:179], v[208:211], v[2:5]
	v_mfma_f32_16x16x32_bf16 v[54:57], v[172:175], v[188:191], v[54:57]
	v_mfma_f32_16x16x32_bf16 v[50:53], v[180:183], v[188:191], v[50:53]
	v_mfma_f32_16x16x32_bf16 v[38:41], v[172:175], v[196:199], v[38:41]
	v_mfma_f32_16x16x32_bf16 v[34:37], v[180:183], v[196:199], v[34:37]
	v_mfma_f32_16x16x32_bf16 v[22:25], v[172:175], v[204:207], v[22:25]
	v_mfma_f32_16x16x32_bf16 v[18:21], v[180:183], v[204:207], v[18:21]
	v_mfma_f32_16x16x32_bf16 v[6:9], v[172:175], v[212:215], v[6:9]
	v_mfma_f32_16x16x32_bf16 v[2:5], v[180:183], v[212:215], v[2:5]
	s_setprio 0
	s_barrier
; #define PG8_STAGE(bufoff, gbase, voff) do { _Pragma("unroll") for (int _i = 0; _i < 2; ++_i) \
;         __builtin_amdgcn_global_load_lds((const unsigned*)((const char*)(gbase) + (voff)[_i]), (PG8_LAS unsigned*)(lds + (bufoff) + ldsw + _i * 8192), 16, 0, 0); } while (0)
; #define PG8_LDA(dst, b, h) do { _Pragma("unroll") for (int m = 0; m < 4; ++m) _Pragma("unroll") for (int k = 0; k < 2; ++k) dst[m][k] = *(const PG8_LAS bf16x8*)(lds + PG8_SA(b, h) + aoff + m * 2048 + k * 1024); } while (0)
; #define PG8_LDB(dst, b, h) do { _Pragma("unroll") for (int n = 0; n < 2; ++n) _Pragma("unroll") for (int k = 0; k < 2; ++k) dst[n][k] = *(const PG8_LAS bf16x8*)(lds + PG8_SB(b, h) + boff + n * 2048 + k * 1024); } while (0)
; #define PG8_MMA(ai, bj, At, Bt) do { __builtin_amdgcn_s_setprio(1); _Pragma("unroll") for (int m = 0; m < 4; ++m) _Pragma("unroll") for (int n = 0; n < 2; ++n) _Pragma("unroll") for (int k = 0; k < 2; ++k) \
;         acc[ai][bj][m][n] = __builtin_amdgcn_mfma_f32_16x16x32_bf16(Bt[n][k], At[m][k], acc[ai][bj][m][n], 0, 0, 0); __builtin_amdgcn_s_setprio(0); } while (0)
; #define PG8_WAIT_V(n) asm volatile("s_waitcnt vmcnt(" #n ")" ::: "memory")
; #define PG8_WAIT_L(n) asm volatile("s_waitcnt lgkmcnt(" #n ")" ::: "memory")
; #define PG8_BAR __builtin_amdgcn_s_barrier()
; #define PG8_SCHED __builtin_amdgcn_sched_barrier(0)
; template <class Epi, class Sched, bool ALIGN_EPI = false, bool SP2 = false, bool KSEG = false>
; __device__ __forceinline__ void gemm_phase(PG8_LAS unsigned char* lds, const Gemm g, const Sched& S, const Epi& E) {
;     ...
;             PG8_LDB(B0, 1, 0); PG8_LDB(B1, 1, 1); PG8_SCHED; PG8_LDA(At, 1, 0); PG8_STAGE(PG8_SA(0, 1), a2 + hstep, voffA);
;             PG8_WAIT_V(8); PG8_WAIT_L(0); PG8_BAR; PG8_MMA(0, 0, At, B0); PG8_MMA(0, 1, At, B1); PG8_BAR; PG8_SCHED;
	s_add_i32 s33, 0, 0x18000
	v_add_u32_e32 v159, s33, v154
	s_add_i32 s81, 0, 0x1c000
	ds_read_b128 v[146:149], v159
	ds_read_b128 v[150:153], v159 offset:1024
	ds_read_b128 v[160:163], v159 offset:2048
	ds_read_b128 v[164:167], v159 offset:3072
	v_add_u32_e32 v159, s81, v154
	ds_read_b128 v[168:171], v159
	ds_read_b128 v[172:175], v159 offset:1024
	ds_read_b128 v[176:179], v159 offset:2048
	ds_read_b128 v[180:183], v159 offset:3072
	s_mov_b32 m0, s27
	v_lshl_add_u64 v[224:225], s[42:43], 0, v[136:137]
	global_load_lds_dwordx4 v[224:225], off
	s_mov_b32 m0, s47
	v_lshl_add_u64 v[224:225], s[42:43], 0, v[132:133]
	global_load_lds_dwordx4 v[224:225], off
	s_add_u32 s42, s42, 0x80000
	s_addc_u32 s43, s43, 0
	s_mov_b32 m0, s48
	v_lshl_add_u64 v[224:225], s[42:43], 0, v[136:137]
	ds_read_b128 v[184:187], v158 offset:32768
	ds_read_b128 v[188:191], v158 offset:33792
	ds_read_b128 v[192:195], v158 offset:34816
	ds_read_b128 v[196:199], v158 offset:35840
	ds_read_b128 v[200:203], v158 offset:36864
	ds_read_b128 v[204:207], v158 offset:37888
	ds_read_b128 v[208:211], v158 offset:38912
	ds_read_b128 v[212:215], v158 offset:39936
	global_load_lds_dwordx4 v[224:225], off
	s_mov_b32 m0, s49
	v_lshl_add_u64 v[224:225], s[42:43], 0, v[132:133]
	global_load_lds_dwordx4 v[224:225], off
	s_waitcnt vmcnt(8) lgkmcnt(0)
	s_barrier
	s_setprio 1
	v_mfma_f32_16x16x32_bf16 v[126:129], v[146:149], v[184:187], v[126:129]
	v_mfma_f32_16x16x32_bf16 v[122:125], v[160:163], v[184:187], v[122:125]
	v_mfma_f32_16x16x32_bf16 v[110:113], v[146:149], v[192:195], v[110:113]
	v_mfma_f32_16x16x32_bf16 v[106:109], v[160:163], v[192:195], v[106:109]
	v_mfma_f32_16x16x32_bf16 v[94:97], v[146:149], v[200:203], v[94:97]
	v_mfma_f32_16x16x32_bf16 v[90:93], v[160:163], v[200:203], v[90:93]
	v_mfma_f32_16x16x32_bf16 v[78:81], v[146:149], v[208:211], v[78:81]
	v_mfma_f32_16x16x32_bf16 v[74:77], v[160:163], v[208:211], v[74:77]
	v_mfma_f32_16x16x32_bf16 v[126:129], v[150:153], v[188:191], v[126:129]
	v_mfma_f32_16x16x32_bf16 v[122:125], v[164:167], v[188:191], v[122:125]
	v_mfma_f32_16x16x32_bf16 v[110:113], v[150:153], v[196:199], v[110:113]
	v_mfma_f32_16x16x32_bf16 v[106:109], v[164:167], v[196:199], v[106:109]
	v_mfma_f32_16x16x32_bf16 v[94:97], v[150:153], v[204:207], v[94:97]
	v_mfma_f32_16x16x32_bf16 v[90:93], v[164:167], v[204:207], v[90:93]
	v_mfma_f32_16x16x32_bf16 v[78:81], v[150:153], v[212:215], v[78:81]
	v_mfma_f32_16x16x32_bf16 v[74:77], v[164:167], v[212:215], v[74:77]
	s_setprio 0
	s_setprio 1
	v_mfma_f32_16x16x32_bf16 v[118:121], v[168:171], v[184:187], v[118:121]
	v_mfma_f32_16x16x32_bf16 v[114:117], v[176:179], v[184:187], v[114:117]
	v_mfma_f32_16x16x32_bf16 v[102:105], v[168:171], v[192:195], v[102:105]
	v_mfma_f32_16x16x32_bf16 v[98:101], v[176:179], v[192:195], v[98:101]
	v_mfma_f32_16x16x32_bf16 v[86:89], v[168:171], v[200:203], v[86:89]
	v_mfma_f32_16x16x32_bf16 v[82:85], v[176:179], v[200:203], v[82:85]
	v_mfma_f32_16x16x32_bf16 v[70:73], v[168:171], v[208:211], v[70:73]
	v_mfma_f32_16x16x32_bf16 v[66:69], v[176:179], v[208:211], v[66:69]
	v_mfma_f32_16x16x32_bf16 v[118:121], v[172:175], v[188:191], v[118:121]
	v_mfma_f32_16x16x32_bf16 v[114:117], v[180:183], v[188:191], v[114:117]
	v_mfma_f32_16x16x32_bf16 v[102:105], v[172:175], v[196:199], v[102:105]
	v_mfma_f32_16x16x32_bf16 v[98:101], v[180:183], v[196:199], v[98:101]
	v_mfma_f32_16x16x32_bf16 v[86:89], v[172:175], v[204:207], v[86:89]
	v_mfma_f32_16x16x32_bf16 v[82:85], v[180:183], v[204:207], v[82:85]
	v_mfma_f32_16x16x32_bf16 v[70:73], v[172:175], v[212:215], v[70:73]
	v_mfma_f32_16x16x32_bf16 v[66:69], v[180:183], v[212:215], v[66:69]
	s_setprio 0
	s_barrier
; #define PG8_STAGE(bufoff, gbase, voff) do { _Pragma("unroll") for (int _i = 0; _i < 2; ++_i) \
;         __builtin_amdgcn_global_load_lds((const unsigned*)((const char*)(gbase) + (voff)[_i]), (PG8_LAS unsigned*)(lds + (bufoff) + ldsw + _i * 8192), 16, 0, 0); } while (0)
; #define PG8_LDA(dst, b, h) do { _Pragma("unroll") for (int m = 0; m < 4; ++m) _Pragma("unroll") for (int k = 0; k < 2; ++k) dst[m][k] = *(const PG8_LAS bf16x8*)(lds + PG8_SA(b, h) + aoff + m * 2048 + k * 1024); } while (0)
; #define PG8_WAIT_V(n) asm volatile("s_waitcnt vmcnt(" #n ")" ::: "memory")
; #define PG8_WAIT_L(n) asm volatile("s_waitcnt lgkmcnt(" #n ")" ::: "memory")
; #define PG8_BAR __builtin_amdgcn_s_barrier()
; template <class Epi, class Sched, bool ALIGN_EPI = false, bool SP2 = false, bool KSEG = false>
; __device__ __forceinline__ void gemm_phase(PG8_LAS unsigned char* lds, const Gemm g, const Sched& S, const Epi& E) {
;     ...
;         for (int t = 0; t < nt; t += 2) {
;             const bool last = (t == nt - 2);
;             const char* a1 = cA + (size_t)(t + 1) * kstep;
;             const char* a2 = last ? nA : cA + (size_t)(t + 2) * kstep; const char* b2 = last ? nB : cB + (size_t)(t + 2) * kstep;
;             const char* a3 = a2 + kstep; const char* b3 = b2 + kstep;
;             if (last && has_next) S.a_ready(nxt);
;             if constexpr (SP2) {
;             PG8_LDB(B0, 0, 0); PG8_LDB(B1, 0, 1); PG8_SCHED; PG8_LDA(At, 0, 0); PG8_STAGE(PG8_SA(1, 1), a1 + hstep, voffA);
;             PG8_WAIT_V(8); PG8_WAIT_L(0); PG8_BAR; PG8_MMA(0, 0, At, B0); PG8_MMA(0, 1, At, B1); PG8_BAR; PG8_SCHED;
;             PG8_LDA(At, 0, 1); PG8_STAGE(PG8_SB(0, 0), b2, voffB); PG8_STAGE(PG8_SB(0, 1), b2 + hstep, voffB); PG8_STAGE(PG8_SA(0, 0), a2, voffA);
;             PG8_WAIT_V(8); PG8_WAIT_L(0); PG8_BAR; PG8_MMA(1, 0, At, B0); PG8_MMA(1, 1, At, B1); PG8_BAR; PG8_SCHED;
;             PG8_LDB(B0, 1, 0); PG8_LDB(B1, 1, 1); PG8_SCHED; PG8_LDA(At, 1, 0); PG8_STAGE(PG8_SA(0, 1), a2 + hstep, voffA);
;             PG8_WAIT_V(8); PG8_WAIT_L(0); PG8_BAR; PG8_MMA(0, 0, At, B0); PG8_MMA(0, 1, At, B1); PG8_BAR; PG8_SCHED;
;             PG8_LDA(At, 1, 1); PG8_STAGE(PG8_SB(1, 0), b3, voffB); PG8_STAGE(PG8_SB(1, 1), b3 + hstep, voffB); PG8_STAGE(PG8_SA(1, 0), a3, voffA);
;             PG8_WAIT_V(8); PG8_WAIT_L(0); PG8_BAR; PG8_MMA(1, 0, At, B0); PG8_MMA(1, 1, At, B1); PG8_BAR; PG8_SCHED;
	s_add_i32 s33, s33, s44
	v_lshl_add_u64 v[216:217], v[216:217], 0, s[12:13]
	s_mov_b32 m0, s33
	ds_read_b128 v[184:187], v158 offset:49152
	ds_read_b128 v[188:191], v158 offset:50176
	ds_read_b128 v[192:195], v158 offset:51200
	ds_read_b128 v[196:199], v158 offset:52224
	ds_read_b128 v[200:203], v158 offset:53248
	ds_read_b128 v[204:207], v158 offset:54272
	ds_read_b128 v[208:211], v158 offset:55296
	ds_read_b128 v[212:215], v158 offset:56320
	global_load_lds_dwordx4 v[216:217], off
	s_add_i32 m0, s33, 0x2000
	s_add_u32 s30, s30, 0x80080
	v_lshl_add_u64 v[216:217], v[218:219], 0, s[12:13]
	s_addc_u32 s31, s31, 0
	s_add_i32 s33, s81, s44
	global_load_lds_dwordx4 v[216:217], off
	s_mov_b32 m0, s33
	v_lshl_add_u64 v[216:217], s[30:31], 0, v[134:135]
	global_load_lds_dwordx4 v[216:217], off
	s_add_i32 m0, s33, 0x2000
	v_lshl_add_u64 v[216:217], s[30:31], 0, v[130:131]
	global_load_lds_dwordx4 v[216:217], off
	s_waitcnt vmcnt(6) lgkmcnt(0)
	s_barrier
	s_setprio 1
	v_mfma_f32_16x16x32_bf16 v[62:65], v[146:149], v[184:187], v[62:65]
	v_mfma_f32_16x16x32_bf16 v[58:61], v[160:163], v[184:187], v[58:61]
	v_mfma_f32_16x16x32_bf16 v[46:49], v[146:149], v[192:195], v[46:49]
	v_mfma_f32_16x16x32_bf16 v[42:45], v[160:163], v[192:195], v[42:45]
	v_mfma_f32_16x16x32_bf16 v[30:33], v[146:149], v[200:203], v[30:33]
	v_mfma_f32_16x16x32_bf16 v[26:29], v[160:163], v[200:203], v[26:29]
	v_mfma_f32_16x16x32_bf16 v[14:17], v[146:149], v[208:211], v[14:17]
	v_mfma_f32_16x16x32_bf16 v[10:13], v[160:163], v[208:211], v[10:13]
	v_mfma_f32_16x16x32_bf16 v[62:65], v[150:153], v[188:191], v[62:65]
	v_mfma_f32_16x16x32_bf16 v[58:61], v[164:167], v[188:191], v[58:61]
	v_mfma_f32_16x16x32_bf16 v[46:49], v[150:153], v[196:199], v[46:49]
	v_mfma_f32_16x16x32_bf16 v[42:45], v[164:167], v[196:199], v[42:45]
	v_mfma_f32_16x16x32_bf16 v[30:33], v[150:153], v[204:207], v[30:33]
	v_mfma_f32_16x16x32_bf16 v[26:29], v[164:167], v[204:207], v[26:29]
	v_mfma_f32_16x16x32_bf16 v[14:17], v[150:153], v[212:215], v[14:17]
	v_mfma_f32_16x16x32_bf16 v[10:13], v[164:167], v[212:215], v[10:13]
	s_setprio 0
	s_setprio 1
	v_mfma_f32_16x16x32_bf16 v[54:57], v[168:171], v[184:187], v[54:57]
	s_add_i32 s80, s80, 2
	v_mfma_f32_16x16x32_bf16 v[50:53], v[176:179], v[184:187], v[50:53]
	s_add_u32 s28, s28, 0x100
	v_mfma_f32_16x16x32_bf16 v[38:41], v[168:171], v[192:195], v[38:41]
	s_addc_u32 s29, s29, 0
	v_mfma_f32_16x16x32_bf16 v[34:37], v[176:179], v[192:195], v[34:37]
	s_add_u32 s66, s66, 0x100
	v_mfma_f32_16x16x32_bf16 v[22:25], v[168:171], v[200:203], v[22:25]
	s_addc_u32 s67, s67, 0
	v_mfma_f32_16x16x32_bf16 v[18:21], v[176:179], v[200:203], v[18:21]
	s_add_u32 s30, s28, 0xfff80080
	v_mfma_f32_16x16x32_bf16 v[6:9], v[168:171], v[208:211], v[6:9]
	s_addc_u32 s31, s29, -1
	v_mfma_f32_16x16x32_bf16 v[2:5], v[176:179], v[208:211], v[2:5]
	s_cmp_eq_u32 s80, 28
	v_mfma_f32_16x16x32_bf16 v[54:57], v[172:175], v[188:191], v[54:57]
	s_cselect_b32 s43, s21, s31
	v_mfma_f32_16x16x32_bf16 v[50:53], v[180:183], v[188:191], v[50:53]
	s_cselect_b32 s42, s64, s30
	v_mfma_f32_16x16x32_bf16 v[38:41], v[172:175], v[196:199], v[38:41]
	s_cselect_b32 s31, s19, s67
	v_mfma_f32_16x16x32_bf16 v[34:37], v[180:183], v[196:199], v[34:37]
	s_cselect_b32 s30, s65, s66
	v_mfma_f32_16x16x32_bf16 v[22:25], v[172:175], v[204:207], v[22:25]
	s_add_u32 s98, s28, 0xfff80000
	v_mfma_f32_16x16x32_bf16 v[18:21], v[180:183], v[204:207], v[18:21]
	s_addc_u32 s99, s29, -1
	v_mfma_f32_16x16x32_bf16 v[6:9], v[172:175], v[212:215], v[6:9]
	s_cmp_gt_u32 s80, 29
	v_mfma_f32_16x16x32_bf16 v[2:5], v[180:183], v[212:215], v[2:5]
	s_setprio 0
	s_barrier
	s_cbranch_scc0 .LBB0_120
	s_and_b64 vcc, exec, s[16:17]
	s_cbranch_vccz .LBB0_123
	s_barrier

; template <class Epi, class Sched, bool ALIGN_EPI = false, bool SP2 = false, bool KSEG = false>
; __device__ __forceinline__ void gemm_phase(PG8_LAS unsigned char* lds, const Gemm g, const Sched& S, const Epi& E) {
;     ...
;         const bool has_next = S.next(ui + 1, nxt);
;         const char* nA = has_next ? (const char*)g.A + (size_t)nxt.pm * tstep : cA; const char* nB = has_next ? (const char*)g.Bt + (size_t)nxt.pn * tstep : cB;
;         for (int t = 0; t < nt; t += 2) {
;             const bool last = (t == nt - 2);
;             const char* a1 = cA + (size_t)(t + 1) * kstep;
;             const char* a2 = last ? nA : cA + (size_t)(t + 2) * kstep; const char* b2 = last ? nB : cB + (size_t)(t + 2) * kstep;
;             const char* a3 = a2 + kstep; const char* b3 = b2 + kstep;
;     ...
; #pragma unroll
;         for (int a = 0; a < 2; ++a)
; #pragma unroll
;             for (int b = 0; b < 2; ++b)
; #pragma unroll
;                 for (int m = 0; m < 4; ++m)
; #pragma unroll
;                     for (int n = 0; n < 2; ++n) acc[a][b][m][n] = (f32x4){0.f, 0.f, 0.f, 0.f};
;         cur = nxt; cA = nA; cB = nB; ++ui;
.LBB0_496:
	s_ashr_i32 s25, s24, 31
	s_lshl_b64 s[26:27], s[24:25], 20
	s_add_u32 s26, s16, s26
	s_addc_u32 s27, s17, s27
	s_and_b64 s[28:29], s[4:5], exec
	s_cselect_b32 s25, s27, s37
	s_cselect_b32 s58, s26, s36
	s_ashr_i32 s23, s22, 31
	s_lshl_b64 s[28:29], s[22:23], 20
	s_add_u32 s28, s76, s28
	s_addc_u32 s29, s77, s29
	s_and_b64 s[40:41], s[4:5], exec
	s_cselect_b32 s23, s29, s39
	s_cselect_b32 s59, s28, s38
	s_add_u32 s36, s36, 0x80080
	s_addc_u32 s37, s37, 0
	s_add_u32 s60, s38, 0x100
	v_mov_b32_e32 v2, 0
	s_addc_u32 s61, s39, 0
	s_mov_b32 s62, -2
	v_mov_b32_e32 v3, v2
	v_mov_b32_e32 v4, v2
	v_mov_b32_e32 v5, v2
	v_mov_b32_e32 v6, v2
	v_mov_b32_e32 v7, v2
	v_mov_b32_e32 v8, v2
	v_mov_b32_e32 v9, v2
	v_mov_b32_e32 v18, v2
	v_mov_b32_e32 v19, v2
	v_mov_b32_e32 v20, v2
	v_mov_b32_e32 v21, v2
	v_mov_b32_e32 v22, v2
	v_mov_b32_e32 v23, v2
	v_mov_b32_e32 v24, v2
	v_mov_b32_e32 v25, v2
	v_mov_b32_e32 v34, v2
	v_mov_b32_e32 v35, v2
	v_mov_b32_e32 v36, v2
	v_mov_b32_e32 v37, v2
	v_mov_b32_e32 v38, v2
	s_waitcnt lgkmcnt(0)
	v_mov_b32_e32 v39, v2
	v_mov_b32_e32 v40, v2
	v_mov_b32_e32 v41, v2
	v_mov_b32_e32 v50, v2
	v_mov_b32_e32 v51, v2
	v_mov_b32_e32 v52, v2
	v_mov_b32_e32 v53, v2
	v_mov_b32_e32 v54, v2
	v_mov_b32_e32 v55, v2
	v_mov_b32_e32 v56, v2
	v_mov_b32_e32 v57, v2
	v_mov_b32_e32 v10, v2
	v_mov_b32_e32 v11, v2
	v_mov_b32_e32 v12, v2
	v_mov_b32_e32 v13, v2
	v_mov_b32_e32 v14, v2
	v_mov_b32_e32 v15, v2
	v_mov_b32_e32 v16, v2
	v_mov_b32_e32 v17, v2
	v_mov_b32_e32 v26, v2
	v_mov_b32_e32 v27, v2
	v_mov_b32_e32 v28, v2
	v_mov_b32_e32 v29, v2
	v_mov_b32_e32 v30, v2
	v_mov_b32_e32 v31, v2
	v_mov_b32_e32 v32, v2
	v_mov_b32_e32 v33, v2
	v_mov_b32_e32 v42, v2
	v_mov_b32_e32 v43, v2
	v_mov_b32_e32 v44, v2
	v_mov_b32_e32 v45, v2
	v_mov_b32_e32 v46, v2
	v_mov_b32_e32 v47, v2
	v_mov_b32_e32 v48, v2
	v_mov_b32_e32 v49, v2
	v_mov_b32_e32 v58, v2
	v_mov_b32_e32 v59, v2
	v_mov_b32_e32 v60, v2
	v_mov_b32_e32 v61, v2
	v_mov_b32_e32 v62, v2
	v_mov_b32_e32 v63, v2
	v_mov_b32_e32 v64, v2
	v_mov_b32_e32 v65, v2
	v_mov_b32_e32 v66, v2
	v_mov_b32_e32 v67, v2
	v_mov_b32_e32 v68, v2
	v_mov_b32_e32 v69, v2
	v_mov_b32_e32 v70, v2
	v_mov_b32_e32 v71, v2
	v_mov_b32_e32 v72, v2
	v_mov_b32_e32 v73, v2
	v_mov_b32_e32 v82, v2
	v_mov_b32_e32 v83, v2
	v_mov_b32_e32 v84, v2
	v_mov_b32_e32 v85, v2
	v_mov_b32_e32 v86, v2
	v_mov_b32_e32 v87, v2
	v_mov_b32_e32 v88, v2
	v_mov_b32_e32 v89, v2
	v_mov_b32_e32 v98, v2
	v_mov_b32_e32 v99, v2
	v_mov_b32_e32 v100, v2
	v_mov_b32_e32 v101, v2
	v_mov_b32_e32 v102, v2
	v_mov_b32_e32 v103, v2
	v_mov_b32_e32 v104, v2
	v_mov_b32_e32 v105, v2
	v_mov_b32_e32 v114, v2
	v_mov_b32_e32 v115, v2
	v_mov_b32_e32 v116, v2
	v_mov_b32_e32 v117, v2
	v_mov_b32_e32 v118, v2
	v_mov_b32_e32 v119, v2
	v_mov_b32_e32 v120, v2
	v_mov_b32_e32 v121, v2
	v_mov_b32_e32 v74, v2
	v_mov_b32_e32 v75, v2
	v_mov_b32_e32 v76, v2
	v_mov_b32_e32 v77, v2
	v_mov_b32_e32 v78, v2
	v_mov_b32_e32 v79, v2
	v_mov_b32_e32 v80, v2
	v_mov_b32_e32 v81, v2
	v_mov_b32_e32 v90, v2
	v_mov_b32_e32 v91, v2
	v_mov_b32_e32 v92, v2
	v_mov_b32_e32 v93, v2
	v_mov_b32_e32 v94, v2
	v_mov_b32_e32 v95, v2
	v_mov_b32_e32 v96, v2
	v_mov_b32_e32 v97, v2
	v_mov_b32_e32 v106, v2
	v_mov_b32_e32 v107, v2
	v_mov_b32_e32 v108, v2
	v_mov_b32_e32 v109, v2
	v_mov_b32_e32 v110, v2
	v_mov_b32_e32 v111, v2
	v_mov_b32_e32 v112, v2
	v_mov_b32_e32 v113, v2
	v_mov_b32_e32 v122, v2
	v_mov_b32_e32 v123, v2
	v_mov_b32_e32 v124, v2
	v_mov_b32_e32 v125, v2
	v_mov_b32_e32 v126, v2
	v_mov_b32_e32 v127, v2
	v_mov_b32_e32 v128, v2
	v_mov_b32_e32 v129, v2
	s_add_u32 s33, s36, 0xfff80080
	s_addc_u32 s38, s37, -1
	s_cmp_eq_u32 s62, 28
	s_cselect_b32 s41, s25, s38
	s_cselect_b32 s40, s58, s33
	s_cselect_b32 s39, s23, s61
	s_cselect_b32 s38, s59, s60
	s_add_u32 s98, s36, 0xfff80000
	s_addc_u32 s99, s37, -1
.LBB0_497:
	ds_read_b128 v[148:151], v168
	ds_read_b128 v[172:175], v168 offset:1024
	ds_read_b128 v[176:179], v168 offset:2048
	ds_read_b128 v[180:183], v168 offset:3072
	ds_read_b128 v[184:187], v169
	ds_read_b128 v[188:191], v169 offset:1024
	ds_read_b128 v[192:195], v169 offset:2048
	ds_read_b128 v[196:199], v169 offset:3072
	s_mov_b32 m0, s52
	v_lshl_add_u64 v[232:233], s[98:99], 0, v[132:133]
	global_load_lds_dwordx4 v[232:233], off
	s_mov_b32 m0, s53
	v_lshl_add_u64 v[232:233], s[98:99], 0, v[136:137]
	global_load_lds_dwordx4 v[232:233], off
	v_lshl_add_u64 v[232:233], s[36:37], 0, v[140:141]
	s_add_i32 m0, s31, 0xc000
	ds_read_b128 v[200:203], v170
	ds_read_b128 v[204:207], v170 offset:1024
	ds_read_b128 v[208:211], v170 offset:2048
	ds_read_b128 v[212:215], v170 offset:3072
	ds_read_b128 v[216:219], v170 offset:4096
	ds_read_b128 v[220:223], v170 offset:5120
	ds_read_b128 v[224:227], v170 offset:6144
	ds_read_b128 v[228:231], v170 offset:7168
	global_load_lds_dwordx4 v[232:233], off
	s_add_i32 m0, s31, 0xe000
	v_lshl_add_u64 v[232:233], s[36:37], 0, v[142:143]
	global_load_lds_dwordx4 v[232:233], off
	s_waitcnt vmcnt(8) lgkmcnt(0)
	s_barrier
; #define PG8_STAGE(bufoff, gbase, voff) do { _Pragma("unroll") for (int _i = 0; _i < 2; ++_i) \
;         __builtin_amdgcn_global_load_lds((const unsigned*)((const char*)(gbase) + (voff)[_i]), (PG8_LAS unsigned*)(lds + (bufoff) + ldsw + _i * 8192), 16, 0, 0); } while (0)
; #define PG8_LDA(dst, b, h) do { _Pragma("unroll") for (int m = 0; m < 4; ++m) _Pragma("unroll") for (int k = 0; k < 2; ++k) dst[m][k] = *(const PG8_LAS bf16x8*)(lds + PG8_SA(b, h) + aoff + m * 2048 + k * 1024); } while (0)
; #define PG8_LDB(dst, b, h) do { _Pragma("unroll") for (int n = 0; n < 2; ++n) _Pragma("unroll") for (int k = 0; k < 2; ++k) dst[n][k] = *(const PG8_LAS bf16x8*)(lds + PG8_SB(b, h) + boff + n * 2048 + k * 1024); } while (0)
; #define PG8_MMA(ai, bj, At, Bt) do { __builtin_amdgcn_s_setprio(1); _Pragma("unroll") for (int m = 0; m < 4; ++m) _Pragma("unroll") for (int n = 0; n < 2; ++n) _Pragma("unroll") for (int k = 0; k < 2; ++k) \
;         acc[ai][bj][m][n] = __builtin_amdgcn_mfma_f32_16x16x32_bf16(Bt[n][k], At[m][k], acc[ai][bj][m][n], 0, 0, 0); __builtin_amdgcn_s_setprio(0); } while (0)
; #define PG8_WAIT_V(n) asm volatile("s_waitcnt vmcnt(" #n ")" ::: "memory")
; #define PG8_WAIT_L(n) asm volatile("s_waitcnt lgkmcnt(" #n ")" ::: "memory")
; #define PG8_BAR __builtin_amdgcn_s_barrier()
; #define PG8_SCHED __builtin_amdgcn_sched_barrier(0)
; template <class Epi, class Sched, bool ALIGN_EPI = false, bool SP2 = false, bool KSEG = false>
; __device__ __forceinline__ void gemm_phase(PG8_LAS unsigned char* lds, const Gemm g, const Sched& S, const Epi& E) {
;     ...
;             PG8_LDB(B0, 0, 0); PG8_LDB(B1, 0, 1); PG8_SCHED; PG8_LDA(At, 0, 0); PG8_STAGE(PG8_SA(1, 1), a1 + hstep, voffA);
;             PG8_WAIT_V(8); PG8_WAIT_L(0); PG8_BAR; PG8_MMA(0, 0, At, B0); PG8_MMA(0, 1, At, B1); PG8_BAR; PG8_SCHED;
;             PG8_LDA(At, 0, 1); PG8_STAGE(PG8_SB(0, 0), b2, voffB); PG8_STAGE(PG8_SB(0, 1), b2 + hstep, voffB); PG8_STAGE(PG8_SA(0, 0), a2, voffA);
;             PG8_WAIT_V(8); PG8_WAIT_L(0); PG8_BAR; PG8_MMA(1, 0, At, B0); PG8_MMA(1, 1, At, B1); PG8_BAR; PG8_SCHED;
	s_setprio 1
	v_mfma_f32_16x16x32_bf16 v[126:129], v[148:151], v[200:203], v[126:129]
	v_mfma_f32_16x16x32_bf16 v[122:125], v[176:179], v[200:203], v[122:125]
	v_mfma_f32_16x16x32_bf16 v[110:113], v[148:151], v[208:211], v[110:113]
	v_mfma_f32_16x16x32_bf16 v[106:109], v[176:179], v[208:211], v[106:109]
	v_mfma_f32_16x16x32_bf16 v[94:97], v[148:151], v[216:219], v[94:97]
	v_mfma_f32_16x16x32_bf16 v[90:93], v[176:179], v[216:219], v[90:93]
	v_mfma_f32_16x16x32_bf16 v[78:81], v[148:151], v[224:227], v[78:81]
	v_mfma_f32_16x16x32_bf16 v[74:77], v[176:179], v[224:227], v[74:77]
	v_mfma_f32_16x16x32_bf16 v[126:129], v[172:175], v[204:207], v[126:129]
	v_mfma_f32_16x16x32_bf16 v[122:125], v[180:183], v[204:207], v[122:125]
	v_mfma_f32_16x16x32_bf16 v[110:113], v[172:175], v[212:215], v[110:113]
	v_mfma_f32_16x16x32_bf16 v[106:109], v[180:183], v[212:215], v[106:109]
	v_mfma_f32_16x16x32_bf16 v[94:97], v[172:175], v[220:223], v[94:97]
	v_mfma_f32_16x16x32_bf16 v[90:93], v[180:183], v[220:223], v[90:93]
	v_mfma_f32_16x16x32_bf16 v[78:81], v[172:175], v[228:231], v[78:81]
	v_mfma_f32_16x16x32_bf16 v[74:77], v[180:183], v[228:231], v[74:77]
	s_setprio 0
	s_setprio 1
	v_mfma_f32_16x16x32_bf16 v[118:121], v[184:187], v[200:203], v[118:121]
	v_mfma_f32_16x16x32_bf16 v[114:117], v[192:195], v[200:203], v[114:117]
	v_mfma_f32_16x16x32_bf16 v[102:105], v[184:187], v[208:211], v[102:105]
	v_mfma_f32_16x16x32_bf16 v[98:101], v[192:195], v[208:211], v[98:101]
	v_mfma_f32_16x16x32_bf16 v[86:89], v[184:187], v[216:219], v[86:89]
	v_mfma_f32_16x16x32_bf16 v[82:85], v[192:195], v[216:219], v[82:85]
	v_mfma_f32_16x16x32_bf16 v[70:73], v[184:187], v[224:227], v[70:73]
	v_mfma_f32_16x16x32_bf16 v[66:69], v[192:195], v[224:227], v[66:69]
	v_mfma_f32_16x16x32_bf16 v[118:121], v[188:191], v[204:207], v[118:121]
	v_mfma_f32_16x16x32_bf16 v[114:117], v[196:199], v[204:207], v[114:117]
	v_mfma_f32_16x16x32_bf16 v[102:105], v[188:191], v[212:215], v[102:105]
	v_mfma_f32_16x16x32_bf16 v[98:101], v[196:199], v[212:215], v[98:101]
	v_mfma_f32_16x16x32_bf16 v[86:89], v[188:191], v[220:223], v[86:89]
	v_mfma_f32_16x16x32_bf16 v[82:85], v[196:199], v[220:223], v[82:85]
	v_mfma_f32_16x16x32_bf16 v[70:73], v[188:191], v[228:231], v[70:73]
	v_mfma_f32_16x16x32_bf16 v[66:69], v[196:199], v[228:231], v[66:69]
	s_setprio 0
	s_barrier
	s_add_i32 s33, s54, s43
	v_lshl_add_u64 v[232:233], s[38:39], 0, v[134:135]
	s_mov_b32 m0, s33
	ds_read_b128 v[200:203], v170 offset:16384
	ds_read_b128 v[204:207], v170 offset:17408
	ds_read_b128 v[208:211], v170 offset:18432
	ds_read_b128 v[212:215], v170 offset:19456
	ds_read_b128 v[216:219], v170 offset:20480
	ds_read_b128 v[220:223], v170 offset:21504
	ds_read_b128 v[224:227], v170 offset:22528
	ds_read_b128 v[228:231], v170 offset:23552
	global_load_lds_dwordx4 v[232:233], off
	s_add_i32 m0, s33, 0x2000
	s_add_u32 s64, s38, 0x80000
	v_lshl_add_u64 v[234:235], s[38:39], 0, v[138:139]
	s_addc_u32 s65, s39, 0
	s_add_i32 s33, s55, s43
	global_load_lds_dwordx4 v[234:235], off
	s_mov_b32 m0, s33
	v_lshl_add_u64 v[236:237], s[64:65], 0, v[134:135]
	global_load_lds_dwordx4 v[236:237], off
	s_add_i32 m0, s33, 0x2000
	v_lshl_add_u64 v[236:237], s[64:65], 0, v[138:139]
	global_load_lds_dwordx4 v[236:237], off
	s_waitcnt vmcnt(6) lgkmcnt(0)
	s_barrier
	s_setprio 1
	v_mfma_f32_16x16x32_bf16 v[62:65], v[148:151], v[200:203], v[62:65]
	v_mfma_f32_16x16x32_bf16 v[58:61], v[176:179], v[200:203], v[58:61]
	v_mfma_f32_16x16x32_bf16 v[46:49], v[148:151], v[208:211], v[46:49]
	v_mfma_f32_16x16x32_bf16 v[42:45], v[176:179], v[208:211], v[42:45]
	v_mfma_f32_16x16x32_bf16 v[30:33], v[148:151], v[216:219], v[30:33]
	v_mfma_f32_16x16x32_bf16 v[26:29], v[176:179], v[216:219], v[26:29]
	v_mfma_f32_16x16x32_bf16 v[14:17], v[148:151], v[224:227], v[14:17]
	v_mfma_f32_16x16x32_bf16 v[10:13], v[176:179], v[224:227], v[10:13]
	v_mfma_f32_16x16x32_bf16 v[62:65], v[172:175], v[204:207], v[62:65]
	v_mfma_f32_16x16x32_bf16 v[58:61], v[180:183], v[204:207], v[58:61]
	v_mfma_f32_16x16x32_bf16 v[46:49], v[172:175], v[212:215], v[46:49]
	v_mfma_f32_16x16x32_bf16 v[42:45], v[180:183], v[212:215], v[42:45]
	v_mfma_f32_16x16x32_bf16 v[30:33], v[172:175], v[220:223], v[30:33]
	v_mfma_f32_16x16x32_bf16 v[26:29], v[180:183], v[220:223], v[26:29]
	v_mfma_f32_16x16x32_bf16 v[14:17], v[172:175], v[228:231], v[14:17]
	v_mfma_f32_16x16x32_bf16 v[10:13], v[180:183], v[228:231], v[10:13]
	s_setprio 0
	s_setprio 1
	v_mfma_f32_16x16x32_bf16 v[54:57], v[184:187], v[200:203], v[54:57]
	v_mfma_f32_16x16x32_bf16 v[50:53], v[192:195], v[200:203], v[50:53]
	v_mfma_f32_16x16x32_bf16 v[38:41], v[184:187], v[208:211], v[38:41]
	v_mfma_f32_16x16x32_bf16 v[34:37], v[192:195], v[208:211], v[34:37]
	v_mfma_f32_16x16x32_bf16 v[22:25], v[184:187], v[216:219], v[22:25]
	v_mfma_f32_16x16x32_bf16 v[18:21], v[192:195], v[216:219], v[18:21]
	v_mfma_f32_16x16x32_bf16 v[6:9], v[184:187], v[224:227], v[6:9]
	v_mfma_f32_16x16x32_bf16 v[2:5], v[192:195], v[224:227], v[2:5]
	v_mfma_f32_16x16x32_bf16 v[54:57], v[188:191], v[204:207], v[54:57]
	v_mfma_f32_16x16x32_bf16 v[50:53], v[196:199], v[204:207], v[50:53]
	v_mfma_f32_16x16x32_bf16 v[38:41], v[188:191], v[212:215], v[38:41]
	v_mfma_f32_16x16x32_bf16 v[34:37], v[196:199], v[212:215], v[34:37]
	v_mfma_f32_16x16x32_bf16 v[22:25], v[188:191], v[220:223], v[22:25]
	v_mfma_f32_16x16x32_bf16 v[18:21], v[196:199], v[220:223], v[18:21]
	v_mfma_f32_16x16x32_bf16 v[6:9], v[188:191], v[228:231], v[6:9]
	v_mfma_f32_16x16x32_bf16 v[2:5], v[196:199], v[228:231], v[2:5]
	s_setprio 0
	s_barrier
; #define PG8_STAGE(bufoff, gbase, voff) do { _Pragma("unroll") for (int _i = 0; _i < 2; ++_i) \
;         __builtin_amdgcn_global_load_lds((const unsigned*)((const char*)(gbase) + (voff)[_i]), (PG8_LAS unsigned*)(lds + (bufoff) + ldsw + _i * 8192), 16, 0, 0); } while (0)
; #define PG8_LDA(dst, b, h) do { _Pragma("unroll") for (int m = 0; m < 4; ++m) _Pragma("unroll") for (int k = 0; k < 2; ++k) dst[m][k] = *(const PG8_LAS bf16x8*)(lds + PG8_SA(b, h) + aoff + m * 2048 + k * 1024); } while (0)
; #define PG8_LDB(dst, b, h) do { _Pragma("unroll") for (int n = 0; n < 2; ++n) _Pragma("unroll") for (int k = 0; k < 2; ++k) dst[n][k] = *(const PG8_LAS bf16x8*)(lds + PG8_SB(b, h) + boff + n * 2048 + k * 1024); } while (0)
; #define PG8_MMA(ai, bj, At, Bt) do { __builtin_amdgcn_s_setprio(1); _Pragma("unroll") for (int m = 0; m < 4; ++m) _Pragma("unroll") for (int n = 0; n < 2; ++n) _Pragma("unroll") for (int k = 0; k < 2; ++k) \
;         acc[ai][bj][m][n] = __builtin_amdgcn_mfma_f32_16x16x32_bf16(Bt[n][k], At[m][k], acc[ai][bj][m][n], 0, 0, 0); __builtin_amdgcn_s_setprio(0); } while (0)
; #define PG8_WAIT_V(n) asm volatile("s_waitcnt vmcnt(" #n ")" ::: "memory")
; #define PG8_WAIT_L(n) asm volatile("s_waitcnt lgkmcnt(" #n ")" ::: "memory")
; #define PG8_BAR __builtin_amdgcn_s_barrier()
; #define PG8_SCHED __builtin_amdgcn_sched_barrier(0)
; template <class Epi, class Sched, bool ALIGN_EPI = false, bool SP2 = false, bool KSEG = false>
; __device__ __forceinline__ void gemm_phase(PG8_LAS unsigned char* lds, const Gemm g, const Sched& S, const Epi& E) {
;     ...
;             PG8_LDB(B0, 1, 0); PG8_LDB(B1, 1, 1); PG8_SCHED; PG8_LDA(At, 1, 0); PG8_STAGE(PG8_SA(0, 1), a2 + hstep, voffA);
;             PG8_WAIT_V(8); PG8_WAIT_L(0); PG8_BAR; PG8_MMA(0, 0, At, B0); PG8_MMA(0, 1, At, B1); PG8_BAR; PG8_SCHED;
	s_add_i32 s33, 0, 0x18000
	s_add_i32 s63, 0, 0x1c000
	v_add_u32_e32 v180, s33, v166
	v_add_u32_e32 v196, s63, v166
	ds_read_b128 v[148:151], v180
	ds_read_b128 v[172:175], v180 offset:1024
	ds_read_b128 v[176:179], v180 offset:2048
	ds_read_b128 v[180:183], v180 offset:3072
	ds_read_b128 v[184:187], v196
	ds_read_b128 v[188:191], v196 offset:1024
	ds_read_b128 v[192:195], v196 offset:2048
	ds_read_b128 v[196:199], v196 offset:3072
	s_mov_b32 m0, s31
	v_lshl_add_u64 v[240:241], s[40:41], 0, v[132:133]
	global_load_lds_dwordx4 v[240:241], off
	s_mov_b32 m0, s45
	v_lshl_add_u64 v[240:241], s[40:41], 0, v[136:137]
	global_load_lds_dwordx4 v[240:241], off
	s_add_u32 s40, s40, 0x80000
	s_addc_u32 s41, s41, 0
	s_mov_b32 m0, s49
	v_lshl_add_u64 v[240:241], s[40:41], 0, v[132:133]
	ds_read_b128 v[200:203], v170 offset:32768
	ds_read_b128 v[204:207], v170 offset:33792
	ds_read_b128 v[208:211], v170 offset:34816
	ds_read_b128 v[212:215], v170 offset:35840
	ds_read_b128 v[216:219], v170 offset:36864
	ds_read_b128 v[220:223], v170 offset:37888
	ds_read_b128 v[224:227], v170 offset:38912
	ds_read_b128 v[228:231], v170 offset:39936
	global_load_lds_dwordx4 v[240:241], off
	s_mov_b32 m0, s50
	v_lshl_add_u64 v[240:241], s[40:41], 0, v[136:137]
	global_load_lds_dwordx4 v[240:241], off
	s_waitcnt vmcnt(8) lgkmcnt(0)
	s_barrier
	s_setprio 1
	v_mfma_f32_16x16x32_bf16 v[126:129], v[148:151], v[200:203], v[126:129]
	v_mfma_f32_16x16x32_bf16 v[122:125], v[176:179], v[200:203], v[122:125]
	v_mfma_f32_16x16x32_bf16 v[110:113], v[148:151], v[208:211], v[110:113]
	v_mfma_f32_16x16x32_bf16 v[106:109], v[176:179], v[208:211], v[106:109]
	v_mfma_f32_16x16x32_bf16 v[94:97], v[148:151], v[216:219], v[94:97]
	v_mfma_f32_16x16x32_bf16 v[90:93], v[176:179], v[216:219], v[90:93]
	v_mfma_f32_16x16x32_bf16 v[78:81], v[148:151], v[224:227], v[78:81]
	v_mfma_f32_16x16x32_bf16 v[74:77], v[176:179], v[224:227], v[74:77]
	v_mfma_f32_16x16x32_bf16 v[126:129], v[172:175], v[204:207], v[126:129]
	v_mfma_f32_16x16x32_bf16 v[122:125], v[180:183], v[204:207], v[122:125]
	v_mfma_f32_16x16x32_bf16 v[110:113], v[172:175], v[212:215], v[110:113]
	v_mfma_f32_16x16x32_bf16 v[106:109], v[180:183], v[212:215], v[106:109]
	v_mfma_f32_16x16x32_bf16 v[94:97], v[172:175], v[220:223], v[94:97]
	v_mfma_f32_16x16x32_bf16 v[90:93], v[180:183], v[220:223], v[90:93]
	v_mfma_f32_16x16x32_bf16 v[78:81], v[172:175], v[228:231], v[78:81]
	v_mfma_f32_16x16x32_bf16 v[74:77], v[180:183], v[228:231], v[74:77]
	s_setprio 0
	s_setprio 1
	v_mfma_f32_16x16x32_bf16 v[118:121], v[184:187], v[200:203], v[118:121]
	v_mfma_f32_16x16x32_bf16 v[114:117], v[192:195], v[200:203], v[114:117]
	v_mfma_f32_16x16x32_bf16 v[102:105], v[184:187], v[208:211], v[102:105]
	v_mfma_f32_16x16x32_bf16 v[98:101], v[192:195], v[208:211], v[98:101]
	v_mfma_f32_16x16x32_bf16 v[86:89], v[184:187], v[216:219], v[86:89]
	v_mfma_f32_16x16x32_bf16 v[82:85], v[192:195], v[216:219], v[82:85]
	v_mfma_f32_16x16x32_bf16 v[70:73], v[184:187], v[224:227], v[70:73]
	v_mfma_f32_16x16x32_bf16 v[66:69], v[192:195], v[224:227], v[66:69]
	v_mfma_f32_16x16x32_bf16 v[118:121], v[188:191], v[204:207], v[118:121]
	v_mfma_f32_16x16x32_bf16 v[114:117], v[196:199], v[204:207], v[114:117]
	v_mfma_f32_16x16x32_bf16 v[102:105], v[188:191], v[212:215], v[102:105]
	v_mfma_f32_16x16x32_bf16 v[98:101], v[196:199], v[212:215], v[98:101]
	v_mfma_f32_16x16x32_bf16 v[86:89], v[188:191], v[220:223], v[86:89]
	v_mfma_f32_16x16x32_bf16 v[82:85], v[196:199], v[220:223], v[82:85]
	v_mfma_f32_16x16x32_bf16 v[70:73], v[188:191], v[228:231], v[70:73]
	v_mfma_f32_16x16x32_bf16 v[66:69], v[196:199], v[228:231], v[66:69]
	s_setprio 0
	s_barrier
; #define PG8_STAGE(bufoff, gbase, voff) do { _Pragma("unroll") for (int _i = 0; _i < 2; ++_i) \
;         __builtin_amdgcn_global_load_lds((const unsigned*)((const char*)(gbase) + (voff)[_i]), (PG8_LAS unsigned*)(lds + (bufoff) + ldsw + _i * 8192), 16, 0, 0); } while (0)
; #define PG8_LDA(dst, b, h) do { _Pragma("unroll") for (int m = 0; m < 4; ++m) _Pragma("unroll") for (int k = 0; k < 2; ++k) dst[m][k] = *(const PG8_LAS bf16x8*)(lds + PG8_SA(b, h) + aoff + m * 2048 + k * 1024); } while (0)
; #define PG8_MMA(ai, bj, At, Bt) do { __builtin_amdgcn_s_setprio(1); _Pragma("unroll") for (int m = 0; m < 4; ++m) _Pragma("unroll") for (int n = 0; n < 2; ++n) _Pragma("unroll") for (int k = 0; k < 2; ++k) \
;         acc[ai][bj][m][n] = __builtin_amdgcn_mfma_f32_16x16x32_bf16(Bt[n][k], At[m][k], acc[ai][bj][m][n], 0, 0, 0); __builtin_amdgcn_s_setprio(0); } while (0)
; #define PG8_WAIT_V(n) asm volatile("s_waitcnt vmcnt(" #n ")" ::: "memory")
; #define PG8_WAIT_L(n) asm volatile("s_waitcnt lgkmcnt(" #n ")" ::: "memory")
; #define PG8_BAR __builtin_amdgcn_s_barrier()
; #define PG8_SCHED __builtin_amdgcn_sched_barrier(0)
; template <class Epi, class Sched, bool ALIGN_EPI = false, bool SP2 = false, bool KSEG = false>
; __device__ __forceinline__ void gemm_phase(PG8_LAS unsigned char* lds, const Gemm g, const Sched& S, const Epi& E) {
;     ...
;         for (int t = 0; t < nt; t += 2) {
;             const bool last = (t == nt - 2);
;             const char* a1 = cA + (size_t)(t + 1) * kstep;
;             const char* a2 = last ? nA : cA + (size_t)(t + 2) * kstep; const char* b2 = last ? nB : cB + (size_t)(t + 2) * kstep;
;             const char* a3 = a2 + kstep; const char* b3 = b2 + kstep;
;     ...
;             PG8_LDA(At, 1, 1); PG8_STAGE(PG8_SB(1, 0), b3, voffB); PG8_STAGE(PG8_SB(1, 1), b3 + hstep, voffB); PG8_STAGE(PG8_SA(1, 0), a3, voffA);
;             PG8_WAIT_V(8); PG8_WAIT_L(0); PG8_BAR; PG8_MMA(1, 0, At, B0); PG8_MMA(1, 1, At, B1); PG8_BAR; PG8_SCHED;
	s_add_i32 s33, s33, s43
	v_lshl_add_u64 v[232:233], v[232:233], 0, s[10:11]
	s_mov_b32 m0, s33
	ds_read_b128 v[200:203], v170 offset:49152
	ds_read_b128 v[204:207], v170 offset:50176
	ds_read_b128 v[208:211], v170 offset:51200
	ds_read_b128 v[212:215], v170 offset:52224
	ds_read_b128 v[216:219], v170 offset:53248
	ds_read_b128 v[220:223], v170 offset:54272
	ds_read_b128 v[224:227], v170 offset:55296
	ds_read_b128 v[228:231], v170 offset:56320
	global_load_lds_dwordx4 v[232:233], off
	s_add_i32 m0, s33, 0x2000
	s_add_u32 s38, s38, 0x80080
	v_lshl_add_u64 v[232:233], v[234:235], 0, s[10:11]
	s_addc_u32 s39, s39, 0
	s_add_i32 s33, s63, s43
	global_load_lds_dwordx4 v[232:233], off
	s_mov_b32 m0, s33
	v_lshl_add_u64 v[232:233], s[38:39], 0, v[134:135]
	global_load_lds_dwordx4 v[232:233], off
	s_add_i32 m0, s33, 0x2000
	v_lshl_add_u64 v[232:233], s[38:39], 0, v[138:139]
	global_load_lds_dwordx4 v[232:233], off
	s_waitcnt vmcnt(6) lgkmcnt(0)
	s_barrier
	s_setprio 1
	v_mfma_f32_16x16x32_bf16 v[62:65], v[148:151], v[200:203], v[62:65]
	v_mfma_f32_16x16x32_bf16 v[58:61], v[176:179], v[200:203], v[58:61]
	v_mfma_f32_16x16x32_bf16 v[46:49], v[148:151], v[208:211], v[46:49]
	v_mfma_f32_16x16x32_bf16 v[42:45], v[176:179], v[208:211], v[42:45]
	v_mfma_f32_16x16x32_bf16 v[30:33], v[148:151], v[216:219], v[30:33]
	v_mfma_f32_16x16x32_bf16 v[26:29], v[176:179], v[216:219], v[26:29]
	v_mfma_f32_16x16x32_bf16 v[14:17], v[148:151], v[224:227], v[14:17]
	v_mfma_f32_16x16x32_bf16 v[10:13], v[176:179], v[224:227], v[10:13]
	v_mfma_f32_16x16x32_bf16 v[62:65], v[172:175], v[204:207], v[62:65]
	v_mfma_f32_16x16x32_bf16 v[58:61], v[180:183], v[204:207], v[58:61]
	v_mfma_f32_16x16x32_bf16 v[46:49], v[172:175], v[212:215], v[46:49]
	v_mfma_f32_16x16x32_bf16 v[42:45], v[180:183], v[212:215], v[42:45]
	v_mfma_f32_16x16x32_bf16 v[30:33], v[172:175], v[220:223], v[30:33]
	v_mfma_f32_16x16x32_bf16 v[26:29], v[180:183], v[220:223], v[26:29]
	v_mfma_f32_16x16x32_bf16 v[14:17], v[172:175], v[228:231], v[14:17]
	v_mfma_f32_16x16x32_bf16 v[10:13], v[180:183], v[228:231], v[10:13]
	s_setprio 0
	s_setprio 1
	v_mfma_f32_16x16x32_bf16 v[54:57], v[184:187], v[200:203], v[54:57]
	s_add_i32 s62, s62, 2
	v_mfma_f32_16x16x32_bf16 v[50:53], v[192:195], v[200:203], v[50:53]
	s_add_u32 s36, s36, 0x100
	v_mfma_f32_16x16x32_bf16 v[38:41], v[184:187], v[208:211], v[38:41]
	s_addc_u32 s37, s37, 0
	v_mfma_f32_16x16x32_bf16 v[34:37], v[192:195], v[208:211], v[34:37]
	s_add_u32 s60, s60, 0x100
	v_mfma_f32_16x16x32_bf16 v[22:25], v[184:187], v[216:219], v[22:25]
	s_addc_u32 s61, s61, 0
	v_mfma_f32_16x16x32_bf16 v[18:21], v[192:195], v[216:219], v[18:21]
	s_add_u32 s33, s36, 0xfff80080
	v_mfma_f32_16x16x32_bf16 v[6:9], v[184:187], v[224:227], v[6:9]
	s_addc_u32 s38, s37, -1
	v_mfma_f32_16x16x32_bf16 v[2:5], v[192:195], v[224:227], v[2:5]
	s_cmp_eq_u32 s62, 28
	v_mfma_f32_16x16x32_bf16 v[54:57], v[188:191], v[204:207], v[54:57]
	s_cselect_b32 s41, s25, s38
	v_mfma_f32_16x16x32_bf16 v[50:53], v[196:199], v[204:207], v[50:53]
	s_cselect_b32 s40, s58, s33
	v_mfma_f32_16x16x32_bf16 v[38:41], v[188:191], v[212:215], v[38:41]
	s_cselect_b32 s39, s23, s61
	v_mfma_f32_16x16x32_bf16 v[34:37], v[196:199], v[212:215], v[34:37]
	s_cselect_b32 s38, s59, s60
	v_mfma_f32_16x16x32_bf16 v[22:25], v[188:191], v[220:223], v[22:25]
	s_add_u32 s98, s36, 0xfff80000
	v_mfma_f32_16x16x32_bf16 v[18:21], v[196:199], v[220:223], v[18:21]
	s_addc_u32 s99, s37, -1
	v_mfma_f32_16x16x32_bf16 v[6:9], v[188:191], v[228:231], v[6:9]
	s_cmp_gt_u32 s62, 29
	v_mfma_f32_16x16x32_bf16 v[2:5], v[196:199], v[228:231], v[2:5]
	s_setprio 0
	s_barrier
	s_cbranch_scc0 .LBB0_497
	s_and_b64 vcc, exec, s[12:13]
	s_cbranch_vccz .LBB0_500
	s_barrier

; template <class Epi, class Sched, bool ALIGN_EPI = false, bool SP2 = false, bool KSEG = false>
; __device__ __forceinline__ void gemm_phase(PG8_LAS unsigned char* lds, const Gemm g, const Sched& S, const Epi& E) {
;     ...
;         for (int t = 0; t < nt; t += 2) {
;             const bool last = (t == nt - 2);
;             const char* a1 = cA + (size_t)(t + 1) * kstep;
;             const char* a2 = last ? nA : cA + (size_t)(t + 2) * kstep; const char* b2 = last ? nB : cB + (size_t)(t + 2) * kstep;
;             const char* a3 = a2 + kstep; const char* b3 = b2 + kstep;
;     ...
; #pragma unroll
;         for (int a = 0; a < 2; ++a)
; #pragma unroll
;             for (int b = 0; b < 2; ++b)
; #pragma unroll
;                 for (int m = 0; m < 4; ++m)
; #pragma unroll
;                     for (int n = 0; n < 2; ++n) acc[a][b][m][n] = (f32x4){0.f, 0.f, 0.f, 0.f};
;         cur = nxt; cA = nA; cB = nB; ++ui;
.LBB0_536:
	s_add_u32 s36, s36, 0x160080
	s_addc_u32 s37, s37, 0
	s_add_u32 s62, s38, 0x100
	v_mov_b32_e32 v2, 0
	s_addc_u32 s63, s39, 0
	s_mov_b32 s64, -2
	v_mov_b32_e32 v3, v2
	v_mov_b32_e32 v4, v2
	v_mov_b32_e32 v5, v2
	v_mov_b32_e32 v6, v2
	v_mov_b32_e32 v7, v2
	v_mov_b32_e32 v8, v2
	v_mov_b32_e32 v9, v2
	v_mov_b32_e32 v18, v2
	v_mov_b32_e32 v19, v2
	v_mov_b32_e32 v20, v2
	v_mov_b32_e32 v21, v2
	v_mov_b32_e32 v22, v2
	v_mov_b32_e32 v23, v2
	v_mov_b32_e32 v24, v2
	v_mov_b32_e32 v25, v2
	v_mov_b32_e32 v34, v2
	v_mov_b32_e32 v35, v2
	v_mov_b32_e32 v36, v2
	v_mov_b32_e32 v37, v2
	v_mov_b32_e32 v38, v2
	s_waitcnt lgkmcnt(0)
	v_mov_b32_e32 v39, v2
	v_mov_b32_e32 v40, v2
	v_mov_b32_e32 v41, v2
	v_mov_b32_e32 v50, v2
	v_mov_b32_e32 v51, v2
	v_mov_b32_e32 v52, v2
	v_mov_b32_e32 v53, v2
	v_mov_b32_e32 v54, v2
	v_mov_b32_e32 v55, v2
	v_mov_b32_e32 v56, v2
	v_mov_b32_e32 v57, v2
	v_mov_b32_e32 v10, v2
	v_mov_b32_e32 v11, v2
	v_mov_b32_e32 v12, v2
	v_mov_b32_e32 v13, v2
	v_mov_b32_e32 v14, v2
	v_mov_b32_e32 v15, v2
	v_mov_b32_e32 v16, v2
	v_mov_b32_e32 v17, v2
	v_mov_b32_e32 v26, v2
	v_mov_b32_e32 v27, v2
	v_mov_b32_e32 v28, v2
	v_mov_b32_e32 v29, v2
	v_mov_b32_e32 v30, v2
	v_mov_b32_e32 v31, v2
	v_mov_b32_e32 v32, v2
	v_mov_b32_e32 v33, v2
	v_mov_b32_e32 v42, v2
	v_mov_b32_e32 v43, v2
	v_mov_b32_e32 v44, v2
	v_mov_b32_e32 v45, v2
	v_mov_b32_e32 v46, v2
	v_mov_b32_e32 v47, v2
	v_mov_b32_e32 v48, v2
	v_mov_b32_e32 v49, v2
	v_mov_b32_e32 v58, v2
	v_mov_b32_e32 v59, v2
	v_mov_b32_e32 v60, v2
	v_mov_b32_e32 v61, v2
	v_mov_b32_e32 v62, v2
	v_mov_b32_e32 v63, v2
	v_mov_b32_e32 v64, v2
	v_mov_b32_e32 v65, v2
	v_mov_b32_e32 v66, v2
	v_mov_b32_e32 v67, v2
	v_mov_b32_e32 v68, v2
	v_mov_b32_e32 v69, v2
	v_mov_b32_e32 v70, v2
	v_mov_b32_e32 v71, v2
	v_mov_b32_e32 v72, v2
	v_mov_b32_e32 v73, v2
	v_mov_b32_e32 v82, v2
	v_mov_b32_e32 v83, v2
	v_mov_b32_e32 v84, v2
	v_mov_b32_e32 v85, v2
	v_mov_b32_e32 v86, v2
	v_mov_b32_e32 v87, v2
	v_mov_b32_e32 v88, v2
	v_mov_b32_e32 v89, v2
	v_mov_b32_e32 v98, v2
	v_mov_b32_e32 v99, v2
	v_mov_b32_e32 v100, v2
	v_mov_b32_e32 v101, v2
	v_mov_b32_e32 v102, v2
	v_mov_b32_e32 v103, v2
	v_mov_b32_e32 v104, v2
	v_mov_b32_e32 v105, v2
	v_mov_b32_e32 v114, v2
	v_mov_b32_e32 v115, v2
	v_mov_b32_e32 v116, v2
	v_mov_b32_e32 v117, v2
	v_mov_b32_e32 v118, v2
	v_mov_b32_e32 v119, v2
	v_mov_b32_e32 v120, v2
	v_mov_b32_e32 v121, v2
	v_mov_b32_e32 v74, v2
	v_mov_b32_e32 v75, v2
	v_mov_b32_e32 v76, v2
	v_mov_b32_e32 v77, v2
	v_mov_b32_e32 v78, v2
	v_mov_b32_e32 v79, v2
	v_mov_b32_e32 v80, v2
	v_mov_b32_e32 v81, v2
	v_mov_b32_e32 v90, v2
	v_mov_b32_e32 v91, v2
	v_mov_b32_e32 v92, v2
	v_mov_b32_e32 v93, v2
	v_mov_b32_e32 v94, v2
	v_mov_b32_e32 v95, v2
	v_mov_b32_e32 v96, v2
	v_mov_b32_e32 v97, v2
	v_mov_b32_e32 v106, v2
	v_mov_b32_e32 v107, v2
	v_mov_b32_e32 v108, v2
	v_mov_b32_e32 v109, v2
	v_mov_b32_e32 v110, v2
	v_mov_b32_e32 v111, v2
	v_mov_b32_e32 v112, v2
	v_mov_b32_e32 v113, v2
	v_mov_b32_e32 v122, v2
	v_mov_b32_e32 v123, v2
	v_mov_b32_e32 v124, v2
	v_mov_b32_e32 v125, v2
	v_mov_b32_e32 v126, v2
	v_mov_b32_e32 v127, v2
	v_mov_b32_e32 v128, v2
	v_mov_b32_e32 v129, v2
	s_add_u32 s33, s36, 0xffea0080
	s_addc_u32 s38, s37, -1
	s_cmpk_eq_i32 s64, 0x54
	s_cselect_b32 s41, s13, s38
	s_cselect_b32 s40, s12, s33
	s_cselect_b32 s39, s31, s63
	s_cselect_b32 s38, s30, s62
	s_add_u32 s98, s36, 0xffea0000
	s_addc_u32 s99, s37, -1
.LBB0_537:
	ds_read_b128 v[154:157], v173
	ds_read_b128 v[176:179], v173 offset:1024
	ds_read_b128 v[180:183], v173 offset:2048
	ds_read_b128 v[184:187], v173 offset:3072
	ds_read_b128 v[188:191], v174
	ds_read_b128 v[192:195], v174 offset:1024
	ds_read_b128 v[196:199], v174 offset:2048
	ds_read_b128 v[200:203], v174 offset:3072
	s_mov_b32 m0, s54
	v_lshl_add_u64 v[236:237], s[98:99], 0, v[140:141]
	global_load_lds_dwordx4 v[236:237], off
	s_mov_b32 m0, s55
	v_lshl_add_u64 v[236:237], s[98:99], 0, v[142:143]
	global_load_lds_dwordx4 v[236:237], off
	v_lshl_add_u64 v[236:237], s[36:37], 0, v[146:147]
	s_add_i32 m0, s44, 0xc000
	ds_read_b128 v[204:207], v175
	ds_read_b128 v[208:211], v175 offset:1024
	ds_read_b128 v[212:215], v175 offset:2048
	ds_read_b128 v[216:219], v175 offset:3072
	ds_read_b128 v[220:223], v175 offset:4096
	ds_read_b128 v[224:227], v175 offset:5120
	ds_read_b128 v[228:231], v175 offset:6144
	ds_read_b128 v[232:235], v175 offset:7168
	global_load_lds_dwordx4 v[236:237], off
	s_add_i32 m0, s44, 0xe000
	v_lshl_add_u64 v[236:237], s[36:37], 0, v[148:149]
	global_load_lds_dwordx4 v[236:237], off
	s_waitcnt vmcnt(8) lgkmcnt(0)
	s_barrier
; #define PG8_STAGE(bufoff, gbase, voff) do { _Pragma("unroll") for (int _i = 0; _i < 2; ++_i) \
;         __builtin_amdgcn_global_load_lds((const unsigned*)((const char*)(gbase) + (voff)[_i]), (PG8_LAS unsigned*)(lds + (bufoff) + ldsw + _i * 8192), 16, 0, 0); } while (0)
; #define PG8_LDA(dst, b, h) do { _Pragma("unroll") for (int m = 0; m < 4; ++m) _Pragma("unroll") for (int k = 0; k < 2; ++k) dst[m][k] = *(const PG8_LAS bf16x8*)(lds + PG8_SA(b, h) + aoff + m * 2048 + k * 1024); } while (0)
; #define PG8_LDB(dst, b, h) do { _Pragma("unroll") for (int n = 0; n < 2; ++n) _Pragma("unroll") for (int k = 0; k < 2; ++k) dst[n][k] = *(const PG8_LAS bf16x8*)(lds + PG8_SB(b, h) + boff + n * 2048 + k * 1024); } while (0)
; #define PG8_MMA(ai, bj, At, Bt) do { __builtin_amdgcn_s_setprio(1); _Pragma("unroll") for (int m = 0; m < 4; ++m) _Pragma("unroll") for (int n = 0; n < 2; ++n) _Pragma("unroll") for (int k = 0; k < 2; ++k) \
;         acc[ai][bj][m][n] = __builtin_amdgcn_mfma_f32_16x16x32_bf16(Bt[n][k], At[m][k], acc[ai][bj][m][n], 0, 0, 0); __builtin_amdgcn_s_setprio(0); } while (0)
; #define PG8_WAIT_V(n) asm volatile("s_waitcnt vmcnt(" #n ")" ::: "memory")
; #define PG8_WAIT_L(n) asm volatile("s_waitcnt lgkmcnt(" #n ")" ::: "memory")
; #define PG8_BAR __builtin_amdgcn_s_barrier()
; #define PG8_SCHED __builtin_amdgcn_sched_barrier(0)
; template <class Epi, class Sched, bool ALIGN_EPI = false, bool SP2 = false, bool KSEG = false>
; __device__ __forceinline__ void gemm_phase(PG8_LAS unsigned char* lds, const Gemm g, const Sched& S, const Epi& E) {
;     ...
;             PG8_LDB(B0, 0, 0); PG8_LDB(B1, 0, 1); PG8_SCHED; PG8_LDA(At, 0, 0); PG8_STAGE(PG8_SA(1, 1), a1 + hstep, voffA);
;             PG8_WAIT_V(8); PG8_WAIT_L(0); PG8_BAR; PG8_MMA(0, 0, At, B0); PG8_MMA(0, 1, At, B1); PG8_BAR; PG8_SCHED;
;             PG8_LDA(At, 0, 1); PG8_STAGE(PG8_SB(0, 0), b2, voffB); PG8_STAGE(PG8_SB(0, 1), b2 + hstep, voffB); PG8_STAGE(PG8_SA(0, 0), a2, voffA);
;             PG8_WAIT_V(8); PG8_WAIT_L(0); PG8_BAR; PG8_MMA(1, 0, At, B0); PG8_MMA(1, 1, At, B1); PG8_BAR; PG8_SCHED;
	s_setprio 1
	v_mfma_f32_16x16x32_bf16 v[126:129], v[154:157], v[204:207], v[126:129]
	v_mfma_f32_16x16x32_bf16 v[122:125], v[180:183], v[204:207], v[122:125]
	v_mfma_f32_16x16x32_bf16 v[110:113], v[154:157], v[212:215], v[110:113]
	v_mfma_f32_16x16x32_bf16 v[106:109], v[180:183], v[212:215], v[106:109]
	v_mfma_f32_16x16x32_bf16 v[94:97], v[154:157], v[220:223], v[94:97]
	v_mfma_f32_16x16x32_bf16 v[90:93], v[180:183], v[220:223], v[90:93]
	v_mfma_f32_16x16x32_bf16 v[78:81], v[154:157], v[228:231], v[78:81]
	v_mfma_f32_16x16x32_bf16 v[74:77], v[180:183], v[228:231], v[74:77]
	v_mfma_f32_16x16x32_bf16 v[126:129], v[176:179], v[208:211], v[126:129]
	v_mfma_f32_16x16x32_bf16 v[122:125], v[184:187], v[208:211], v[122:125]
	v_mfma_f32_16x16x32_bf16 v[110:113], v[176:179], v[216:219], v[110:113]
	v_mfma_f32_16x16x32_bf16 v[106:109], v[184:187], v[216:219], v[106:109]
	v_mfma_f32_16x16x32_bf16 v[94:97], v[176:179], v[224:227], v[94:97]
	v_mfma_f32_16x16x32_bf16 v[90:93], v[184:187], v[224:227], v[90:93]
	v_mfma_f32_16x16x32_bf16 v[78:81], v[176:179], v[232:235], v[78:81]
	v_mfma_f32_16x16x32_bf16 v[74:77], v[184:187], v[232:235], v[74:77]
	s_setprio 0
	s_setprio 1
	v_mfma_f32_16x16x32_bf16 v[118:121], v[188:191], v[204:207], v[118:121]
	v_mfma_f32_16x16x32_bf16 v[114:117], v[196:199], v[204:207], v[114:117]
	v_mfma_f32_16x16x32_bf16 v[102:105], v[188:191], v[212:215], v[102:105]
	v_mfma_f32_16x16x32_bf16 v[98:101], v[196:199], v[212:215], v[98:101]
	v_mfma_f32_16x16x32_bf16 v[86:89], v[188:191], v[220:223], v[86:89]
	v_mfma_f32_16x16x32_bf16 v[82:85], v[196:199], v[220:223], v[82:85]
	v_mfma_f32_16x16x32_bf16 v[70:73], v[188:191], v[228:231], v[70:73]
	v_mfma_f32_16x16x32_bf16 v[66:69], v[196:199], v[228:231], v[66:69]
	v_mfma_f32_16x16x32_bf16 v[118:121], v[192:195], v[208:211], v[118:121]
	v_mfma_f32_16x16x32_bf16 v[114:117], v[200:203], v[208:211], v[114:117]
	v_mfma_f32_16x16x32_bf16 v[102:105], v[192:195], v[216:219], v[102:105]
	v_mfma_f32_16x16x32_bf16 v[98:101], v[200:203], v[216:219], v[98:101]
	v_mfma_f32_16x16x32_bf16 v[86:89], v[192:195], v[224:227], v[86:89]
	v_mfma_f32_16x16x32_bf16 v[82:85], v[200:203], v[224:227], v[82:85]
	v_mfma_f32_16x16x32_bf16 v[70:73], v[192:195], v[232:235], v[70:73]
	v_mfma_f32_16x16x32_bf16 v[66:69], v[200:203], v[232:235], v[66:69]
	s_setprio 0
	s_barrier
	s_add_i32 s33, s56, s43
	v_lshl_add_u64 v[236:237], s[38:39], 0, v[130:131]
	s_mov_b32 m0, s33
	ds_read_b128 v[204:207], v175 offset:16384
	ds_read_b128 v[208:211], v175 offset:17408
	ds_read_b128 v[212:215], v175 offset:18432
	ds_read_b128 v[216:219], v175 offset:19456
	ds_read_b128 v[220:223], v175 offset:20480
	ds_read_b128 v[224:227], v175 offset:21504
	ds_read_b128 v[228:231], v175 offset:22528
	ds_read_b128 v[232:235], v175 offset:23552
	global_load_lds_dwordx4 v[236:237], off
	s_add_i32 m0, s33, 0x2000
	s_add_u32 s66, s38, 0x160000
	v_lshl_add_u64 v[238:239], s[38:39], 0, v[144:145]
	s_addc_u32 s67, s39, 0
	s_add_i32 s33, s57, s43
	global_load_lds_dwordx4 v[238:239], off
	s_mov_b32 m0, s33
	v_lshl_add_u64 v[240:241], s[66:67], 0, v[130:131]
	global_load_lds_dwordx4 v[240:241], off
	s_add_i32 m0, s33, 0x2000
	v_lshl_add_u64 v[240:241], s[66:67], 0, v[144:145]
	global_load_lds_dwordx4 v[240:241], off
	s_waitcnt vmcnt(6) lgkmcnt(0)
	s_barrier
	s_setprio 1
	v_mfma_f32_16x16x32_bf16 v[62:65], v[154:157], v[204:207], v[62:65]
	v_mfma_f32_16x16x32_bf16 v[58:61], v[180:183], v[204:207], v[58:61]
	v_mfma_f32_16x16x32_bf16 v[46:49], v[154:157], v[212:215], v[46:49]
	v_mfma_f32_16x16x32_bf16 v[42:45], v[180:183], v[212:215], v[42:45]
	v_mfma_f32_16x16x32_bf16 v[30:33], v[154:157], v[220:223], v[30:33]
	v_mfma_f32_16x16x32_bf16 v[26:29], v[180:183], v[220:223], v[26:29]
	v_mfma_f32_16x16x32_bf16 v[14:17], v[154:157], v[228:231], v[14:17]
	v_mfma_f32_16x16x32_bf16 v[10:13], v[180:183], v[228:231], v[10:13]
	v_mfma_f32_16x16x32_bf16 v[62:65], v[176:179], v[208:211], v[62:65]
	v_mfma_f32_16x16x32_bf16 v[58:61], v[184:187], v[208:211], v[58:61]
	v_mfma_f32_16x16x32_bf16 v[46:49], v[176:179], v[216:219], v[46:49]
	v_mfma_f32_16x16x32_bf16 v[42:45], v[184:187], v[216:219], v[42:45]
	v_mfma_f32_16x16x32_bf16 v[30:33], v[176:179], v[224:227], v[30:33]
	v_mfma_f32_16x16x32_bf16 v[26:29], v[184:187], v[224:227], v[26:29]
	v_mfma_f32_16x16x32_bf16 v[14:17], v[176:179], v[232:235], v[14:17]
	v_mfma_f32_16x16x32_bf16 v[10:13], v[184:187], v[232:235], v[10:13]
	s_setprio 0
	s_setprio 1
	v_mfma_f32_16x16x32_bf16 v[54:57], v[188:191], v[204:207], v[54:57]
	v_mfma_f32_16x16x32_bf16 v[50:53], v[196:199], v[204:207], v[50:53]
	v_mfma_f32_16x16x32_bf16 v[38:41], v[188:191], v[212:215], v[38:41]
	v_mfma_f32_16x16x32_bf16 v[34:37], v[196:199], v[212:215], v[34:37]
	v_mfma_f32_16x16x32_bf16 v[22:25], v[188:191], v[220:223], v[22:25]
	v_mfma_f32_16x16x32_bf16 v[18:21], v[196:199], v[220:223], v[18:21]
	v_mfma_f32_16x16x32_bf16 v[6:9], v[188:191], v[228:231], v[6:9]
	v_mfma_f32_16x16x32_bf16 v[2:5], v[196:199], v[228:231], v[2:5]
	v_mfma_f32_16x16x32_bf16 v[54:57], v[192:195], v[208:211], v[54:57]
	v_mfma_f32_16x16x32_bf16 v[50:53], v[200:203], v[208:211], v[50:53]
	v_mfma_f32_16x16x32_bf16 v[38:41], v[192:195], v[216:219], v[38:41]
	v_mfma_f32_16x16x32_bf16 v[34:37], v[200:203], v[216:219], v[34:37]
	v_mfma_f32_16x16x32_bf16 v[22:25], v[192:195], v[224:227], v[22:25]
	v_mfma_f32_16x16x32_bf16 v[18:21], v[200:203], v[224:227], v[18:21]
	v_mfma_f32_16x16x32_bf16 v[6:9], v[192:195], v[232:235], v[6:9]
	v_mfma_f32_16x16x32_bf16 v[2:5], v[200:203], v[232:235], v[2:5]
	s_setprio 0
	s_barrier
; #define PG8_STAGE(bufoff, gbase, voff) do { _Pragma("unroll") for (int _i = 0; _i < 2; ++_i) \
;         __builtin_amdgcn_global_load_lds((const unsigned*)((const char*)(gbase) + (voff)[_i]), (PG8_LAS unsigned*)(lds + (bufoff) + ldsw + _i * 8192), 16, 0, 0); } while (0)
; #define PG8_LDA(dst, b, h) do { _Pragma("unroll") for (int m = 0; m < 4; ++m) _Pragma("unroll") for (int k = 0; k < 2; ++k) dst[m][k] = *(const PG8_LAS bf16x8*)(lds + PG8_SA(b, h) + aoff + m * 2048 + k * 1024); } while (0)
; #define PG8_LDB(dst, b, h) do { _Pragma("unroll") for (int n = 0; n < 2; ++n) _Pragma("unroll") for (int k = 0; k < 2; ++k) dst[n][k] = *(const PG8_LAS bf16x8*)(lds + PG8_SB(b, h) + boff + n * 2048 + k * 1024); } while (0)
; #define PG8_MMA(ai, bj, At, Bt) do { __builtin_amdgcn_s_setprio(1); _Pragma("unroll") for (int m = 0; m < 4; ++m) _Pragma("unroll") for (int n = 0; n < 2; ++n) _Pragma("unroll") for (int k = 0; k < 2; ++k) \
;         acc[ai][bj][m][n] = __builtin_amdgcn_mfma_f32_16x16x32_bf16(Bt[n][k], At[m][k], acc[ai][bj][m][n], 0, 0, 0); __builtin_amdgcn_s_setprio(0); } while (0)
; #define PG8_WAIT_V(n) asm volatile("s_waitcnt vmcnt(" #n ")" ::: "memory")
; #define PG8_WAIT_L(n) asm volatile("s_waitcnt lgkmcnt(" #n ")" ::: "memory")
; #define PG8_BAR __builtin_amdgcn_s_barrier()
; #define PG8_SCHED __builtin_amdgcn_sched_barrier(0)
; template <class Epi, class Sched, bool ALIGN_EPI = false, bool SP2 = false, bool KSEG = false>
; __device__ __forceinline__ void gemm_phase(PG8_LAS unsigned char* lds, const Gemm g, const Sched& S, const Epi& E) {
;     ...
;             PG8_LDB(B0, 1, 0); PG8_LDB(B1, 1, 1); PG8_SCHED; PG8_LDA(At, 1, 0); PG8_STAGE(PG8_SA(0, 1), a2 + hstep, voffA);
;             PG8_WAIT_V(8); PG8_WAIT_L(0); PG8_BAR; PG8_MMA(0, 0, At, B0); PG8_MMA(0, 1, At, B1); PG8_BAR; PG8_SCHED;
	s_add_i32 s33, 0, 0x18000
	s_add_i32 s65, 0, 0x1c000
	v_add_u32_e32 v184, s33, v171
	v_add_u32_e32 v200, s65, v171
	ds_read_b128 v[154:157], v184
	ds_read_b128 v[176:179], v184 offset:1024
	ds_read_b128 v[180:183], v184 offset:2048
	ds_read_b128 v[184:187], v184 offset:3072
	ds_read_b128 v[188:191], v200
	ds_read_b128 v[192:195], v200 offset:1024
	ds_read_b128 v[196:199], v200 offset:2048
	ds_read_b128 v[200:203], v200 offset:3072
	s_mov_b32 m0, s44
	v_lshl_add_u64 v[244:245], s[40:41], 0, v[140:141]
	global_load_lds_dwordx4 v[244:245], off
	s_mov_b32 m0, s45
	v_lshl_add_u64 v[244:245], s[40:41], 0, v[142:143]
	global_load_lds_dwordx4 v[244:245], off
	s_add_u32 s40, s40, 0x160000
	s_addc_u32 s41, s41, 0
	s_mov_b32 m0, s51
	v_lshl_add_u64 v[244:245], s[40:41], 0, v[140:141]
	ds_read_b128 v[204:207], v175 offset:32768
	ds_read_b128 v[208:211], v175 offset:33792
	ds_read_b128 v[212:215], v175 offset:34816
	ds_read_b128 v[216:219], v175 offset:35840
	ds_read_b128 v[220:223], v175 offset:36864
	ds_read_b128 v[224:227], v175 offset:37888
	ds_read_b128 v[228:231], v175 offset:38912
	ds_read_b128 v[232:235], v175 offset:39936
	global_load_lds_dwordx4 v[244:245], off
	s_mov_b32 m0, s52
	v_lshl_add_u64 v[244:245], s[40:41], 0, v[142:143]
	global_load_lds_dwordx4 v[244:245], off
	s_waitcnt vmcnt(8) lgkmcnt(0)
	s_barrier
	s_setprio 1
	v_mfma_f32_16x16x32_bf16 v[126:129], v[154:157], v[204:207], v[126:129]
	v_mfma_f32_16x16x32_bf16 v[122:125], v[180:183], v[204:207], v[122:125]
	v_mfma_f32_16x16x32_bf16 v[110:113], v[154:157], v[212:215], v[110:113]
	v_mfma_f32_16x16x32_bf16 v[106:109], v[180:183], v[212:215], v[106:109]
	v_mfma_f32_16x16x32_bf16 v[94:97], v[154:157], v[220:223], v[94:97]
	v_mfma_f32_16x16x32_bf16 v[90:93], v[180:183], v[220:223], v[90:93]
	v_mfma_f32_16x16x32_bf16 v[78:81], v[154:157], v[228:231], v[78:81]
	v_mfma_f32_16x16x32_bf16 v[74:77], v[180:183], v[228:231], v[74:77]
	v_mfma_f32_16x16x32_bf16 v[126:129], v[176:179], v[208:211], v[126:129]
	v_mfma_f32_16x16x32_bf16 v[122:125], v[184:187], v[208:211], v[122:125]
	v_mfma_f32_16x16x32_bf16 v[110:113], v[176:179], v[216:219], v[110:113]
	v_mfma_f32_16x16x32_bf16 v[106:109], v[184:187], v[216:219], v[106:109]
	v_mfma_f32_16x16x32_bf16 v[94:97], v[176:179], v[224:227], v[94:97]
	v_mfma_f32_16x16x32_bf16 v[90:93], v[184:187], v[224:227], v[90:93]
	v_mfma_f32_16x16x32_bf16 v[78:81], v[176:179], v[232:235], v[78:81]
	v_mfma_f32_16x16x32_bf16 v[74:77], v[184:187], v[232:235], v[74:77]
	s_setprio 0
	s_setprio 1
	v_mfma_f32_16x16x32_bf16 v[118:121], v[188:191], v[204:207], v[118:121]
	v_mfma_f32_16x16x32_bf16 v[114:117], v[196:199], v[204:207], v[114:117]
	v_mfma_f32_16x16x32_bf16 v[102:105], v[188:191], v[212:215], v[102:105]
	v_mfma_f32_16x16x32_bf16 v[98:101], v[196:199], v[212:215], v[98:101]
	v_mfma_f32_16x16x32_bf16 v[86:89], v[188:191], v[220:223], v[86:89]
	v_mfma_f32_16x16x32_bf16 v[82:85], v[196:199], v[220:223], v[82:85]
	v_mfma_f32_16x16x32_bf16 v[70:73], v[188:191], v[228:231], v[70:73]
	v_mfma_f32_16x16x32_bf16 v[66:69], v[196:199], v[228:231], v[66:69]
	v_mfma_f32_16x16x32_bf16 v[118:121], v[192:195], v[208:211], v[118:121]
	v_mfma_f32_16x16x32_bf16 v[114:117], v[200:203], v[208:211], v[114:117]
	v_mfma_f32_16x16x32_bf16 v[102:105], v[192:195], v[216:219], v[102:105]
	v_mfma_f32_16x16x32_bf16 v[98:101], v[200:203], v[216:219], v[98:101]
	v_mfma_f32_16x16x32_bf16 v[86:89], v[192:195], v[224:227], v[86:89]
	v_mfma_f32_16x16x32_bf16 v[82:85], v[200:203], v[224:227], v[82:85]
	v_mfma_f32_16x16x32_bf16 v[70:73], v[192:195], v[232:235], v[70:73]
	v_mfma_f32_16x16x32_bf16 v[66:69], v[200:203], v[232:235], v[66:69]
	s_setprio 0
	s_barrier
; #define PG8_STAGE(bufoff, gbase, voff) do { _Pragma("unroll") for (int _i = 0; _i < 2; ++_i) \
;         __builtin_amdgcn_global_load_lds((const unsigned*)((const char*)(gbase) + (voff)[_i]), (PG8_LAS unsigned*)(lds + (bufoff) + ldsw + _i * 8192), 16, 0, 0); } while (0)
; #define PG8_LDA(dst, b, h) do { _Pragma("unroll") for (int m = 0; m < 4; ++m) _Pragma("unroll") for (int k = 0; k < 2; ++k) dst[m][k] = *(const PG8_LAS bf16x8*)(lds + PG8_SA(b, h) + aoff + m * 2048 + k * 1024); } while (0)
; #define PG8_MMA(ai, bj, At, Bt) do { __builtin_amdgcn_s_setprio(1); _Pragma("unroll") for (int m = 0; m < 4; ++m) _Pragma("unroll") for (int n = 0; n < 2; ++n) _Pragma("unroll") for (int k = 0; k < 2; ++k) \
;         acc[ai][bj][m][n] = __builtin_amdgcn_mfma_f32_16x16x32_bf16(Bt[n][k], At[m][k], acc[ai][bj][m][n], 0, 0, 0); __builtin_amdgcn_s_setprio(0); } while (0)
; #define PG8_WAIT_V(n) asm volatile("s_waitcnt vmcnt(" #n ")" ::: "memory")
; #define PG8_WAIT_L(n) asm volatile("s_waitcnt lgkmcnt(" #n ")" ::: "memory")
; #define PG8_BAR __builtin_amdgcn_s_barrier()
; #define PG8_SCHED __builtin_amdgcn_sched_barrier(0)
; template <class Epi, class Sched, bool ALIGN_EPI = false, bool SP2 = false, bool KSEG = false>
; __device__ __forceinline__ void gemm_phase(PG8_LAS unsigned char* lds, const Gemm g, const Sched& S, const Epi& E) {
;     ...
;         for (int t = 0; t < nt; t += 2) {
;             const bool last = (t == nt - 2);
;             const char* a1 = cA + (size_t)(t + 1) * kstep;
;             const char* a2 = last ? nA : cA + (size_t)(t + 2) * kstep; const char* b2 = last ? nB : cB + (size_t)(t + 2) * kstep;
;             const char* a3 = a2 + kstep; const char* b3 = b2 + kstep;
;     ...
;             PG8_LDA(At, 1, 1); PG8_STAGE(PG8_SB(1, 0), b3, voffB); PG8_STAGE(PG8_SB(1, 1), b3 + hstep, voffB); PG8_STAGE(PG8_SA(1, 0), a3, voffA);
;             PG8_WAIT_V(8); PG8_WAIT_L(0); PG8_BAR; PG8_MMA(1, 0, At, B0); PG8_MMA(1, 1, At, B1); PG8_BAR; PG8_SCHED;
	s_add_i32 s33, s33, s43
	v_lshl_add_u64 v[236:237], v[236:237], 0, s[26:27]
	s_mov_b32 m0, s33
	ds_read_b128 v[204:207], v175 offset:49152
	ds_read_b128 v[208:211], v175 offset:50176
	ds_read_b128 v[212:215], v175 offset:51200
	ds_read_b128 v[216:219], v175 offset:52224
	ds_read_b128 v[220:223], v175 offset:53248
	ds_read_b128 v[224:227], v175 offset:54272
	ds_read_b128 v[228:231], v175 offset:55296
	ds_read_b128 v[232:235], v175 offset:56320
	global_load_lds_dwordx4 v[236:237], off
	s_add_i32 m0, s33, 0x2000
	s_add_u32 s38, s38, 0x160080
	v_lshl_add_u64 v[236:237], v[238:239], 0, s[26:27]
	s_addc_u32 s39, s39, 0
	s_add_i32 s33, s65, s43
	global_load_lds_dwordx4 v[236:237], off
	s_mov_b32 m0, s33
	v_lshl_add_u64 v[236:237], s[38:39], 0, v[130:131]
	global_load_lds_dwordx4 v[236:237], off
	s_add_i32 m0, s33, 0x2000
	v_lshl_add_u64 v[236:237], s[38:39], 0, v[144:145]
	global_load_lds_dwordx4 v[236:237], off
	s_waitcnt vmcnt(6) lgkmcnt(0)
	s_barrier
	s_setprio 1
	v_mfma_f32_16x16x32_bf16 v[62:65], v[154:157], v[204:207], v[62:65]
	v_mfma_f32_16x16x32_bf16 v[58:61], v[180:183], v[204:207], v[58:61]
	v_mfma_f32_16x16x32_bf16 v[46:49], v[154:157], v[212:215], v[46:49]
	v_mfma_f32_16x16x32_bf16 v[42:45], v[180:183], v[212:215], v[42:45]
	v_mfma_f32_16x16x32_bf16 v[30:33], v[154:157], v[220:223], v[30:33]
	v_mfma_f32_16x16x32_bf16 v[26:29], v[180:183], v[220:223], v[26:29]
	v_mfma_f32_16x16x32_bf16 v[14:17], v[154:157], v[228:231], v[14:17]
	v_mfma_f32_16x16x32_bf16 v[10:13], v[180:183], v[228:231], v[10:13]
	v_mfma_f32_16x16x32_bf16 v[62:65], v[176:179], v[208:211], v[62:65]
	v_mfma_f32_16x16x32_bf16 v[58:61], v[184:187], v[208:211], v[58:61]
	v_mfma_f32_16x16x32_bf16 v[46:49], v[176:179], v[216:219], v[46:49]
	v_mfma_f32_16x16x32_bf16 v[42:45], v[184:187], v[216:219], v[42:45]
	v_mfma_f32_16x16x32_bf16 v[30:33], v[176:179], v[224:227], v[30:33]
	v_mfma_f32_16x16x32_bf16 v[26:29], v[184:187], v[224:227], v[26:29]
	v_mfma_f32_16x16x32_bf16 v[14:17], v[176:179], v[232:235], v[14:17]
	v_mfma_f32_16x16x32_bf16 v[10:13], v[184:187], v[232:235], v[10:13]
	s_setprio 0
	s_setprio 1
	v_mfma_f32_16x16x32_bf16 v[54:57], v[188:191], v[204:207], v[54:57]
	s_add_i32 s64, s64, 2
	v_mfma_f32_16x16x32_bf16 v[50:53], v[196:199], v[204:207], v[50:53]
	s_add_u32 s36, s36, 0x100
	v_mfma_f32_16x16x32_bf16 v[38:41], v[188:191], v[212:215], v[38:41]
	s_addc_u32 s37, s37, 0
	v_mfma_f32_16x16x32_bf16 v[34:37], v[196:199], v[212:215], v[34:37]
	s_add_u32 s62, s62, 0x100
	v_mfma_f32_16x16x32_bf16 v[22:25], v[188:191], v[220:223], v[22:25]
	s_addc_u32 s63, s63, 0
	v_mfma_f32_16x16x32_bf16 v[18:21], v[196:199], v[220:223], v[18:21]
	s_add_u32 s33, s36, 0xffea0080
	v_mfma_f32_16x16x32_bf16 v[6:9], v[188:191], v[228:231], v[6:9]
	s_addc_u32 s38, s37, -1
	v_mfma_f32_16x16x32_bf16 v[2:5], v[196:199], v[228:231], v[2:5]
	s_cmpk_eq_i32 s64, 0x54
	v_mfma_f32_16x16x32_bf16 v[54:57], v[192:195], v[208:211], v[54:57]
	s_cselect_b32 s41, s13, s38
	v_mfma_f32_16x16x32_bf16 v[50:53], v[200:203], v[208:211], v[50:53]
	s_cselect_b32 s40, s12, s33
	v_mfma_f32_16x16x32_bf16 v[38:41], v[192:195], v[216:219], v[38:41]
	s_cselect_b32 s39, s31, s63
	v_mfma_f32_16x16x32_bf16 v[34:37], v[200:203], v[216:219], v[34:37]
	s_cselect_b32 s38, s30, s62
	v_mfma_f32_16x16x32_bf16 v[22:25], v[192:195], v[224:227], v[22:25]
	s_add_u32 s98, s36, 0xffea0000
	v_mfma_f32_16x16x32_bf16 v[18:21], v[200:203], v[224:227], v[18:21]
	s_addc_u32 s99, s37, -1
	v_mfma_f32_16x16x32_bf16 v[6:9], v[192:195], v[232:235], v[6:9]
	s_cmpk_gt_u32 s64, 0x55
	v_mfma_f32_16x16x32_bf16 v[2:5], v[200:203], v[232:235], v[2:5]
	s_setprio 0
	s_barrier
	s_cbranch_scc0 .LBB0_537
	s_and_b64 vcc, exec, s[28:29]
	s_cbranch_vccz .LBB0_540
	s_barrier

; template <class Epi, class Sched, bool ALIGN_EPI = false, bool SP2 = false, bool KSEG = false>
; __device__ __forceinline__ void gemm_phase(PG8_LAS unsigned char* lds, const Gemm g, const Sched& S, const Epi& E) {
;     ...
;         const bool has_next = S.next(ui + 1, nxt);
;         const char* nA = has_next ? (const char*)g.A + (size_t)nxt.pm * tstep : cA; const char* nB = has_next ? (const char*)g.Bt + (size_t)nxt.pn * tstep : cB;
;         for (int t = 0; t < nt; t += 2) {
;             const bool last = (t == nt - 2);
;             const char* a1 = cA + (size_t)(t + 1) * kstep;
;             const char* a2 = last ? nA : cA + (size_t)(t + 2) * kstep; const char* b2 = last ? nB : cB + (size_t)(t + 2) * kstep;
;             const char* a3 = a2 + kstep; const char* b3 = b2 + kstep;
;     ...
; #pragma unroll
;         for (int a = 0; a < 2; ++a)
; #pragma unroll
;             for (int b = 0; b < 2; ++b)
; #pragma unroll
;                 for (int m = 0; m < 4; ++m)
; #pragma unroll
;                     for (int n = 0; n < 2; ++n) acc[a][b][m][n] = (f32x4){0.f, 0.f, 0.f, 0.f};
;         cur = nxt; cA = nA; cB = nB; ++ui;
.LBB0_580:
	s_ashr_i32 s29, s28, 31
	s_lshl_b64 s[30:31], s[28:29], 20
	s_add_u32 s30, s51, s30
	v_cmp_lt_i64_e64 s[6:7], s[6:7], v[150:151]
	s_addc_u32 s31, s52, s31
	s_and_b64 s[36:37], s[6:7], exec
	s_cselect_b32 s29, s31, s41
	s_cselect_b32 s65, s30, s40
	s_ashr_i32 s27, s26, 31
	s_lshl_b64 s[36:37], s[26:27], 20
	s_add_u32 s36, s76, s36
	s_addc_u32 s37, s77, s37
	s_and_b64 s[44:45], s[6:7], exec
	s_cselect_b32 s27, s37, s43
	s_cselect_b32 s66, s36, s42
	s_add_u32 s40, s40, 0x80080
	s_addc_u32 s41, s41, 0
	s_add_u32 s67, s42, 0x100
	v_mov_b32_e32 v2, 0
	s_addc_u32 s78, s43, 0
	s_mov_b32 s79, -2
	v_mov_b32_e32 v3, v2
	v_mov_b32_e32 v4, v2
	v_mov_b32_e32 v5, v2
	v_mov_b32_e32 v6, v2
	v_mov_b32_e32 v7, v2
	v_mov_b32_e32 v8, v2
	v_mov_b32_e32 v9, v2
	v_mov_b32_e32 v18, v2
	v_mov_b32_e32 v19, v2
	v_mov_b32_e32 v20, v2
	v_mov_b32_e32 v21, v2
	v_mov_b32_e32 v22, v2
	v_mov_b32_e32 v23, v2
	v_mov_b32_e32 v24, v2
	v_mov_b32_e32 v25, v2
	v_mov_b32_e32 v34, v2
	v_mov_b32_e32 v35, v2
	v_mov_b32_e32 v36, v2
	v_mov_b32_e32 v37, v2
	v_mov_b32_e32 v38, v2
	s_waitcnt lgkmcnt(0)
	v_mov_b32_e32 v39, v2
	v_mov_b32_e32 v40, v2
	v_mov_b32_e32 v41, v2
	v_mov_b32_e32 v50, v2
	v_mov_b32_e32 v51, v2
	v_mov_b32_e32 v52, v2
	v_mov_b32_e32 v53, v2
	v_mov_b32_e32 v54, v2
	v_mov_b32_e32 v55, v2
	v_mov_b32_e32 v56, v2
	v_mov_b32_e32 v57, v2
	v_mov_b32_e32 v10, v2
	v_mov_b32_e32 v11, v2
	v_mov_b32_e32 v12, v2
	v_mov_b32_e32 v13, v2
	v_mov_b32_e32 v14, v2
	v_mov_b32_e32 v15, v2
	v_mov_b32_e32 v16, v2
	v_mov_b32_e32 v17, v2
	v_mov_b32_e32 v26, v2
	v_mov_b32_e32 v27, v2
	v_mov_b32_e32 v28, v2
	v_mov_b32_e32 v29, v2
	v_mov_b32_e32 v30, v2
	v_mov_b32_e32 v31, v2
	v_mov_b32_e32 v32, v2
	v_mov_b32_e32 v33, v2
	v_mov_b32_e32 v42, v2
	v_mov_b32_e32 v43, v2
	v_mov_b32_e32 v44, v2
	v_mov_b32_e32 v45, v2
	v_mov_b32_e32 v46, v2
	v_mov_b32_e32 v47, v2
	v_mov_b32_e32 v48, v2
	v_mov_b32_e32 v49, v2
	v_mov_b32_e32 v58, v2
	v_mov_b32_e32 v59, v2
	v_mov_b32_e32 v60, v2
	v_mov_b32_e32 v61, v2
	v_mov_b32_e32 v62, v2
	v_mov_b32_e32 v63, v2
	v_mov_b32_e32 v64, v2
	v_mov_b32_e32 v65, v2
	v_mov_b32_e32 v66, v2
	v_mov_b32_e32 v67, v2
	v_mov_b32_e32 v68, v2
	v_mov_b32_e32 v69, v2
	v_mov_b32_e32 v70, v2
	v_mov_b32_e32 v71, v2
	v_mov_b32_e32 v72, v2
	v_mov_b32_e32 v73, v2
	v_mov_b32_e32 v82, v2
	v_mov_b32_e32 v83, v2
	v_mov_b32_e32 v84, v2
	v_mov_b32_e32 v85, v2
	v_mov_b32_e32 v86, v2
	v_mov_b32_e32 v87, v2
	v_mov_b32_e32 v88, v2
	v_mov_b32_e32 v89, v2
	v_mov_b32_e32 v98, v2
	v_mov_b32_e32 v99, v2
	v_mov_b32_e32 v100, v2
	v_mov_b32_e32 v101, v2
	v_mov_b32_e32 v102, v2
	v_mov_b32_e32 v103, v2
	v_mov_b32_e32 v104, v2
	v_mov_b32_e32 v105, v2
	v_mov_b32_e32 v114, v2
	v_mov_b32_e32 v115, v2
	v_mov_b32_e32 v116, v2
	v_mov_b32_e32 v117, v2
	v_mov_b32_e32 v118, v2
	v_mov_b32_e32 v119, v2
	v_mov_b32_e32 v120, v2
	v_mov_b32_e32 v121, v2
	v_mov_b32_e32 v74, v2
	v_mov_b32_e32 v75, v2
	v_mov_b32_e32 v76, v2
	v_mov_b32_e32 v77, v2
	v_mov_b32_e32 v78, v2
	v_mov_b32_e32 v79, v2
	v_mov_b32_e32 v80, v2
	v_mov_b32_e32 v81, v2
	v_mov_b32_e32 v90, v2
	v_mov_b32_e32 v91, v2
	v_mov_b32_e32 v92, v2
	v_mov_b32_e32 v93, v2
	v_mov_b32_e32 v94, v2
	v_mov_b32_e32 v95, v2
	v_mov_b32_e32 v96, v2
	v_mov_b32_e32 v97, v2
	v_mov_b32_e32 v106, v2
	v_mov_b32_e32 v107, v2
	v_mov_b32_e32 v108, v2
	v_mov_b32_e32 v109, v2
	v_mov_b32_e32 v110, v2
	v_mov_b32_e32 v111, v2
	v_mov_b32_e32 v112, v2
	v_mov_b32_e32 v113, v2
	v_mov_b32_e32 v122, v2
	v_mov_b32_e32 v123, v2
	v_mov_b32_e32 v124, v2
	v_mov_b32_e32 v125, v2
	v_mov_b32_e32 v126, v2
	v_mov_b32_e32 v127, v2
	v_mov_b32_e32 v128, v2
	v_mov_b32_e32 v129, v2
	s_add_u32 s33, s40, 0xfff80080
	s_addc_u32 s42, s41, -1
	s_cmp_eq_u32 s79, 28
	s_cselect_b32 s45, s29, s42
	s_cselect_b32 s44, s65, s33
	s_cselect_b32 s43, s27, s78
	s_cselect_b32 s42, s66, s67
	s_add_u32 s98, s40, 0xfff80000
	s_addc_u32 s99, s41, -1
.LBB0_581:
	ds_read_b128 v[154:157], v160
	ds_read_b128 v[172:175], v160 offset:1024
	ds_read_b128 v[176:179], v160 offset:2048
	ds_read_b128 v[180:183], v160 offset:3072
	ds_read_b128 v[184:187], v161
	ds_read_b128 v[188:191], v161 offset:1024
	ds_read_b128 v[192:195], v161 offset:2048
	ds_read_b128 v[196:199], v161 offset:3072
	s_mov_b32 m0, s60
	v_lshl_add_u64 v[232:233], s[98:99], 0, v[132:133]
	global_load_lds_dwordx4 v[232:233], off
	s_mov_b32 m0, s61
	v_lshl_add_u64 v[232:233], s[98:99], 0, v[136:137]
	global_load_lds_dwordx4 v[232:233], off
	v_lshl_add_u64 v[232:233], s[40:41], 0, v[146:147]
	s_add_i32 m0, s55, 0xc000
	ds_read_b128 v[200:203], v164
	ds_read_b128 v[204:207], v164 offset:1024
	ds_read_b128 v[208:211], v164 offset:2048
	ds_read_b128 v[212:215], v164 offset:3072
	ds_read_b128 v[216:219], v164 offset:4096
	ds_read_b128 v[220:223], v164 offset:5120
	ds_read_b128 v[224:227], v164 offset:6144
	ds_read_b128 v[228:231], v164 offset:7168
	global_load_lds_dwordx4 v[232:233], off
	s_add_i32 m0, s55, 0xe000
	v_lshl_add_u64 v[232:233], s[40:41], 0, v[148:149]
	global_load_lds_dwordx4 v[232:233], off
	s_waitcnt vmcnt(8) lgkmcnt(0)
	s_barrier
; #define PG8_STAGE(bufoff, gbase, voff) do { _Pragma("unroll") for (int _i = 0; _i < 2; ++_i) \
;         __builtin_amdgcn_global_load_lds((const unsigned*)((const char*)(gbase) + (voff)[_i]), (PG8_LAS unsigned*)(lds + (bufoff) + ldsw + _i * 8192), 16, 0, 0); } while (0)
; #define PG8_LDA(dst, b, h) do { _Pragma("unroll") for (int m = 0; m < 4; ++m) _Pragma("unroll") for (int k = 0; k < 2; ++k) dst[m][k] = *(const PG8_LAS bf16x8*)(lds + PG8_SA(b, h) + aoff + m * 2048 + k * 1024); } while (0)
; #define PG8_LDB(dst, b, h) do { _Pragma("unroll") for (int n = 0; n < 2; ++n) _Pragma("unroll") for (int k = 0; k < 2; ++k) dst[n][k] = *(const PG8_LAS bf16x8*)(lds + PG8_SB(b, h) + boff + n * 2048 + k * 1024); } while (0)
; #define PG8_MMA(ai, bj, At, Bt) do { __builtin_amdgcn_s_setprio(1); _Pragma("unroll") for (int m = 0; m < 4; ++m) _Pragma("unroll") for (int n = 0; n < 2; ++n) _Pragma("unroll") for (int k = 0; k < 2; ++k) \
;         acc[ai][bj][m][n] = __builtin_amdgcn_mfma_f32_16x16x32_bf16(Bt[n][k], At[m][k], acc[ai][bj][m][n], 0, 0, 0); __builtin_amdgcn_s_setprio(0); } while (0)
; #define PG8_WAIT_V(n) asm volatile("s_waitcnt vmcnt(" #n ")" ::: "memory")
; #define PG8_WAIT_L(n) asm volatile("s_waitcnt lgkmcnt(" #n ")" ::: "memory")
; #define PG8_BAR __builtin_amdgcn_s_barrier()
; #define PG8_SCHED __builtin_amdgcn_sched_barrier(0)
; template <class Epi, class Sched, bool ALIGN_EPI = false, bool SP2 = false, bool KSEG = false>
; __device__ __forceinline__ void gemm_phase(PG8_LAS unsigned char* lds, const Gemm g, const Sched& S, const Epi& E) {
;     ...
;             PG8_LDB(B0, 0, 0); PG8_LDB(B1, 0, 1); PG8_SCHED; PG8_LDA(At, 0, 0); PG8_STAGE(PG8_SA(1, 1), a1 + hstep, voffA);
;             PG8_WAIT_V(8); PG8_WAIT_L(0); PG8_BAR; PG8_MMA(0, 0, At, B0); PG8_MMA(0, 1, At, B1); PG8_BAR; PG8_SCHED;
;             PG8_LDA(At, 0, 1); PG8_STAGE(PG8_SB(0, 0), b2, voffB); PG8_STAGE(PG8_SB(0, 1), b2 + hstep, voffB); PG8_STAGE(PG8_SA(0, 0), a2, voffA);
;             PG8_WAIT_V(8); PG8_WAIT_L(0); PG8_BAR; PG8_MMA(1, 0, At, B0); PG8_MMA(1, 1, At, B1); PG8_BAR; PG8_SCHED;
	s_setprio 1
	v_mfma_f32_16x16x32_bf16 v[126:129], v[154:157], v[200:203], v[126:129]
	v_mfma_f32_16x16x32_bf16 v[122:125], v[176:179], v[200:203], v[122:125]
	v_mfma_f32_16x16x32_bf16 v[110:113], v[154:157], v[208:211], v[110:113]
	v_mfma_f32_16x16x32_bf16 v[106:109], v[176:179], v[208:211], v[106:109]
	v_mfma_f32_16x16x32_bf16 v[94:97], v[154:157], v[216:219], v[94:97]
	v_mfma_f32_16x16x32_bf16 v[90:93], v[176:179], v[216:219], v[90:93]
	v_mfma_f32_16x16x32_bf16 v[78:81], v[154:157], v[224:227], v[78:81]
	v_mfma_f32_16x16x32_bf16 v[74:77], v[176:179], v[224:227], v[74:77]
	v_mfma_f32_16x16x32_bf16 v[126:129], v[172:175], v[204:207], v[126:129]
	v_mfma_f32_16x16x32_bf16 v[122:125], v[180:183], v[204:207], v[122:125]
	v_mfma_f32_16x16x32_bf16 v[110:113], v[172:175], v[212:215], v[110:113]
	v_mfma_f32_16x16x32_bf16 v[106:109], v[180:183], v[212:215], v[106:109]
	v_mfma_f32_16x16x32_bf16 v[94:97], v[172:175], v[220:223], v[94:97]
	v_mfma_f32_16x16x32_bf16 v[90:93], v[180:183], v[220:223], v[90:93]
	v_mfma_f32_16x16x32_bf16 v[78:81], v[172:175], v[228:231], v[78:81]
	v_mfma_f32_16x16x32_bf16 v[74:77], v[180:183], v[228:231], v[74:77]
	s_setprio 0
	s_setprio 1
	v_mfma_f32_16x16x32_bf16 v[118:121], v[184:187], v[200:203], v[118:121]
	v_mfma_f32_16x16x32_bf16 v[114:117], v[192:195], v[200:203], v[114:117]
	v_mfma_f32_16x16x32_bf16 v[102:105], v[184:187], v[208:211], v[102:105]
	v_mfma_f32_16x16x32_bf16 v[98:101], v[192:195], v[208:211], v[98:101]
	v_mfma_f32_16x16x32_bf16 v[86:89], v[184:187], v[216:219], v[86:89]
	v_mfma_f32_16x16x32_bf16 v[82:85], v[192:195], v[216:219], v[82:85]
	v_mfma_f32_16x16x32_bf16 v[70:73], v[184:187], v[224:227], v[70:73]
	v_mfma_f32_16x16x32_bf16 v[66:69], v[192:195], v[224:227], v[66:69]
	v_mfma_f32_16x16x32_bf16 v[118:121], v[188:191], v[204:207], v[118:121]
	v_mfma_f32_16x16x32_bf16 v[114:117], v[196:199], v[204:207], v[114:117]
	v_mfma_f32_16x16x32_bf16 v[102:105], v[188:191], v[212:215], v[102:105]
	v_mfma_f32_16x16x32_bf16 v[98:101], v[196:199], v[212:215], v[98:101]
	v_mfma_f32_16x16x32_bf16 v[86:89], v[188:191], v[220:223], v[86:89]
	v_mfma_f32_16x16x32_bf16 v[82:85], v[196:199], v[220:223], v[82:85]
	v_mfma_f32_16x16x32_bf16 v[70:73], v[188:191], v[228:231], v[70:73]
	v_mfma_f32_16x16x32_bf16 v[66:69], v[196:199], v[228:231], v[66:69]
	s_setprio 0
	s_barrier
	s_add_i32 s33, s62, s53
	v_lshl_add_u64 v[232:233], s[42:43], 0, v[134:135]
	s_mov_b32 m0, s33
	ds_read_b128 v[200:203], v164 offset:16384
	ds_read_b128 v[204:207], v164 offset:17408
	ds_read_b128 v[208:211], v164 offset:18432
	ds_read_b128 v[212:215], v164 offset:19456
	ds_read_b128 v[216:219], v164 offset:20480
	ds_read_b128 v[220:223], v164 offset:21504
	ds_read_b128 v[224:227], v164 offset:22528
	ds_read_b128 v[228:231], v164 offset:23552
	global_load_lds_dwordx4 v[232:233], off
	s_add_i32 m0, s33, 0x2000
	s_add_u32 s80, s42, 0x80000
	v_lshl_add_u64 v[234:235], s[42:43], 0, v[138:139]
	s_addc_u32 s81, s43, 0
	s_add_i32 s33, s63, s53
	global_load_lds_dwordx4 v[234:235], off
	s_mov_b32 m0, s33
	v_lshl_add_u64 v[236:237], s[80:81], 0, v[134:135]
	global_load_lds_dwordx4 v[236:237], off
	s_add_i32 m0, s33, 0x2000
	v_lshl_add_u64 v[236:237], s[80:81], 0, v[138:139]
	global_load_lds_dwordx4 v[236:237], off
	s_waitcnt vmcnt(6) lgkmcnt(0)
	s_barrier
	s_setprio 1
	v_mfma_f32_16x16x32_bf16 v[62:65], v[154:157], v[200:203], v[62:65]
	v_mfma_f32_16x16x32_bf16 v[58:61], v[176:179], v[200:203], v[58:61]
	v_mfma_f32_16x16x32_bf16 v[46:49], v[154:157], v[208:211], v[46:49]
	v_mfma_f32_16x16x32_bf16 v[42:45], v[176:179], v[208:211], v[42:45]
	v_mfma_f32_16x16x32_bf16 v[30:33], v[154:157], v[216:219], v[30:33]
	v_mfma_f32_16x16x32_bf16 v[26:29], v[176:179], v[216:219], v[26:29]
	v_mfma_f32_16x16x32_bf16 v[14:17], v[154:157], v[224:227], v[14:17]
	v_mfma_f32_16x16x32_bf16 v[10:13], v[176:179], v[224:227], v[10:13]
	v_mfma_f32_16x16x32_bf16 v[62:65], v[172:175], v[204:207], v[62:65]
	v_mfma_f32_16x16x32_bf16 v[58:61], v[180:183], v[204:207], v[58:61]
	v_mfma_f32_16x16x32_bf16 v[46:49], v[172:175], v[212:215], v[46:49]
	v_mfma_f32_16x16x32_bf16 v[42:45], v[180:183], v[212:215], v[42:45]
	v_mfma_f32_16x16x32_bf16 v[30:33], v[172:175], v[220:223], v[30:33]
	v_mfma_f32_16x16x32_bf16 v[26:29], v[180:183], v[220:223], v[26:29]
	v_mfma_f32_16x16x32_bf16 v[14:17], v[172:175], v[228:231], v[14:17]
	v_mfma_f32_16x16x32_bf16 v[10:13], v[180:183], v[228:231], v[10:13]
	s_setprio 0
	s_setprio 1
	v_mfma_f32_16x16x32_bf16 v[54:57], v[184:187], v[200:203], v[54:57]
	v_mfma_f32_16x16x32_bf16 v[50:53], v[192:195], v[200:203], v[50:53]
	v_mfma_f32_16x16x32_bf16 v[38:41], v[184:187], v[208:211], v[38:41]
	v_mfma_f32_16x16x32_bf16 v[34:37], v[192:195], v[208:211], v[34:37]
	v_mfma_f32_16x16x32_bf16 v[22:25], v[184:187], v[216:219], v[22:25]
	v_mfma_f32_16x16x32_bf16 v[18:21], v[192:195], v[216:219], v[18:21]
	v_mfma_f32_16x16x32_bf16 v[6:9], v[184:187], v[224:227], v[6:9]
	v_mfma_f32_16x16x32_bf16 v[2:5], v[192:195], v[224:227], v[2:5]
	v_mfma_f32_16x16x32_bf16 v[54:57], v[188:191], v[204:207], v[54:57]
	v_mfma_f32_16x16x32_bf16 v[50:53], v[196:199], v[204:207], v[50:53]
	v_mfma_f32_16x16x32_bf16 v[38:41], v[188:191], v[212:215], v[38:41]
	v_mfma_f32_16x16x32_bf16 v[34:37], v[196:199], v[212:215], v[34:37]
	v_mfma_f32_16x16x32_bf16 v[22:25], v[188:191], v[220:223], v[22:25]
	v_mfma_f32_16x16x32_bf16 v[18:21], v[196:199], v[220:223], v[18:21]
	v_mfma_f32_16x16x32_bf16 v[6:9], v[188:191], v[228:231], v[6:9]
	v_mfma_f32_16x16x32_bf16 v[2:5], v[196:199], v[228:231], v[2:5]
	s_setprio 0
	s_barrier
; #define PG8_STAGE(bufoff, gbase, voff) do { _Pragma("unroll") for (int _i = 0; _i < 2; ++_i) \
;         __builtin_amdgcn_global_load_lds((const unsigned*)((const char*)(gbase) + (voff)[_i]), (PG8_LAS unsigned*)(lds + (bufoff) + ldsw + _i * 8192), 16, 0, 0); } while (0)
; #define PG8_LDA(dst, b, h) do { _Pragma("unroll") for (int m = 0; m < 4; ++m) _Pragma("unroll") for (int k = 0; k < 2; ++k) dst[m][k] = *(const PG8_LAS bf16x8*)(lds + PG8_SA(b, h) + aoff + m * 2048 + k * 1024); } while (0)
; #define PG8_LDB(dst, b, h) do { _Pragma("unroll") for (int n = 0; n < 2; ++n) _Pragma("unroll") for (int k = 0; k < 2; ++k) dst[n][k] = *(const PG8_LAS bf16x8*)(lds + PG8_SB(b, h) + boff + n * 2048 + k * 1024); } while (0)
; #define PG8_MMA(ai, bj, At, Bt) do { __builtin_amdgcn_s_setprio(1); _Pragma("unroll") for (int m = 0; m < 4; ++m) _Pragma("unroll") for (int n = 0; n < 2; ++n) _Pragma("unroll") for (int k = 0; k < 2; ++k) \
;         acc[ai][bj][m][n] = __builtin_amdgcn_mfma_f32_16x16x32_bf16(Bt[n][k], At[m][k], acc[ai][bj][m][n], 0, 0, 0); __builtin_amdgcn_s_setprio(0); } while (0)
; #define PG8_WAIT_V(n) asm volatile("s_waitcnt vmcnt(" #n ")" ::: "memory")
; #define PG8_WAIT_L(n) asm volatile("s_waitcnt lgkmcnt(" #n ")" ::: "memory")
; #define PG8_BAR __builtin_amdgcn_s_barrier()
; #define PG8_SCHED __builtin_amdgcn_sched_barrier(0)
; template <class Epi, class Sched, bool ALIGN_EPI = false, bool SP2 = false, bool KSEG = false>
; __device__ __forceinline__ void gemm_phase(PG8_LAS unsigned char* lds, const Gemm g, const Sched& S, const Epi& E) {
;     ...
;             PG8_LDB(B0, 1, 0); PG8_LDB(B1, 1, 1); PG8_SCHED; PG8_LDA(At, 1, 0); PG8_STAGE(PG8_SA(0, 1), a2 + hstep, voffA);
;             PG8_WAIT_V(8); PG8_WAIT_L(0); PG8_BAR; PG8_MMA(0, 0, At, B0); PG8_MMA(0, 1, At, B1); PG8_BAR; PG8_SCHED;
	s_add_i32 s33, 0, 0x18000
	s_add_i32 s80, 0, 0x1c000
	v_add_u32_e32 v180, s33, v163
	v_add_u32_e32 v196, s80, v163
	ds_read_b128 v[154:157], v180
	ds_read_b128 v[172:175], v180 offset:1024
	ds_read_b128 v[176:179], v180 offset:2048
	ds_read_b128 v[180:183], v180 offset:3072
	ds_read_b128 v[184:187], v196
	ds_read_b128 v[188:191], v196 offset:1024
	ds_read_b128 v[192:195], v196 offset:2048
	ds_read_b128 v[196:199], v196 offset:3072
	s_mov_b32 m0, s55
	v_lshl_add_u64 v[240:241], s[44:45], 0, v[132:133]
	global_load_lds_dwordx4 v[240:241], off
	s_mov_b32 m0, s56
	v_lshl_add_u64 v[240:241], s[44:45], 0, v[136:137]
	global_load_lds_dwordx4 v[240:241], off
	s_add_u32 s44, s44, 0x80000
	s_addc_u32 s45, s45, 0
	s_mov_b32 m0, s57
	v_lshl_add_u64 v[240:241], s[44:45], 0, v[132:133]
	ds_read_b128 v[200:203], v164 offset:32768
	ds_read_b128 v[204:207], v164 offset:33792
	ds_read_b128 v[208:211], v164 offset:34816
	ds_read_b128 v[212:215], v164 offset:35840
	ds_read_b128 v[216:219], v164 offset:36864
	ds_read_b128 v[220:223], v164 offset:37888
	ds_read_b128 v[224:227], v164 offset:38912
	ds_read_b128 v[228:231], v164 offset:39936
	global_load_lds_dwordx4 v[240:241], off
	s_mov_b32 m0, s58
	v_lshl_add_u64 v[240:241], s[44:45], 0, v[136:137]
	global_load_lds_dwordx4 v[240:241], off
	s_waitcnt vmcnt(8) lgkmcnt(0)
	s_barrier
	s_setprio 1
	v_mfma_f32_16x16x32_bf16 v[126:129], v[154:157], v[200:203], v[126:129]
	v_mfma_f32_16x16x32_bf16 v[122:125], v[176:179], v[200:203], v[122:125]
	v_mfma_f32_16x16x32_bf16 v[110:113], v[154:157], v[208:211], v[110:113]
	v_mfma_f32_16x16x32_bf16 v[106:109], v[176:179], v[208:211], v[106:109]
	v_mfma_f32_16x16x32_bf16 v[94:97], v[154:157], v[216:219], v[94:97]
	v_mfma_f32_16x16x32_bf16 v[90:93], v[176:179], v[216:219], v[90:93]
	v_mfma_f32_16x16x32_bf16 v[78:81], v[154:157], v[224:227], v[78:81]
	v_mfma_f32_16x16x32_bf16 v[74:77], v[176:179], v[224:227], v[74:77]
	v_mfma_f32_16x16x32_bf16 v[126:129], v[172:175], v[204:207], v[126:129]
	v_mfma_f32_16x16x32_bf16 v[122:125], v[180:183], v[204:207], v[122:125]
	v_mfma_f32_16x16x32_bf16 v[110:113], v[172:175], v[212:215], v[110:113]
	v_mfma_f32_16x16x32_bf16 v[106:109], v[180:183], v[212:215], v[106:109]
	v_mfma_f32_16x16x32_bf16 v[94:97], v[172:175], v[220:223], v[94:97]
	v_mfma_f32_16x16x32_bf16 v[90:93], v[180:183], v[220:223], v[90:93]
	v_mfma_f32_16x16x32_bf16 v[78:81], v[172:175], v[228:231], v[78:81]
	v_mfma_f32_16x16x32_bf16 v[74:77], v[180:183], v[228:231], v[74:77]
	s_setprio 0
	s_setprio 1
	v_mfma_f32_16x16x32_bf16 v[118:121], v[184:187], v[200:203], v[118:121]
	v_mfma_f32_16x16x32_bf16 v[114:117], v[192:195], v[200:203], v[114:117]
	v_mfma_f32_16x16x32_bf16 v[102:105], v[184:187], v[208:211], v[102:105]
	v_mfma_f32_16x16x32_bf16 v[98:101], v[192:195], v[208:211], v[98:101]
	v_mfma_f32_16x16x32_bf16 v[86:89], v[184:187], v[216:219], v[86:89]
	v_mfma_f32_16x16x32_bf16 v[82:85], v[192:195], v[216:219], v[82:85]
	v_mfma_f32_16x16x32_bf16 v[70:73], v[184:187], v[224:227], v[70:73]
	v_mfma_f32_16x16x32_bf16 v[66:69], v[192:195], v[224:227], v[66:69]
	v_mfma_f32_16x16x32_bf16 v[118:121], v[188:191], v[204:207], v[118:121]
	v_mfma_f32_16x16x32_bf16 v[114:117], v[196:199], v[204:207], v[114:117]
	v_mfma_f32_16x16x32_bf16 v[102:105], v[188:191], v[212:215], v[102:105]
	v_mfma_f32_16x16x32_bf16 v[98:101], v[196:199], v[212:215], v[98:101]
	v_mfma_f32_16x16x32_bf16 v[86:89], v[188:191], v[220:223], v[86:89]
	v_mfma_f32_16x16x32_bf16 v[82:85], v[196:199], v[220:223], v[82:85]
	v_mfma_f32_16x16x32_bf16 v[70:73], v[188:191], v[228:231], v[70:73]
	v_mfma_f32_16x16x32_bf16 v[66:69], v[196:199], v[228:231], v[66:69]
	s_setprio 0
	s_barrier
; #define PG8_STAGE(bufoff, gbase, voff) do { _Pragma("unroll") for (int _i = 0; _i < 2; ++_i) \
;         __builtin_amdgcn_global_load_lds((const unsigned*)((const char*)(gbase) + (voff)[_i]), (PG8_LAS unsigned*)(lds + (bufoff) + ldsw + _i * 8192), 16, 0, 0); } while (0)
; #define PG8_LDA(dst, b, h) do { _Pragma("unroll") for (int m = 0; m < 4; ++m) _Pragma("unroll") for (int k = 0; k < 2; ++k) dst[m][k] = *(const PG8_LAS bf16x8*)(lds + PG8_SA(b, h) + aoff + m * 2048 + k * 1024); } while (0)
; #define PG8_MMA(ai, bj, At, Bt) do { __builtin_amdgcn_s_setprio(1); _Pragma("unroll") for (int m = 0; m < 4; ++m) _Pragma("unroll") for (int n = 0; n < 2; ++n) _Pragma("unroll") for (int k = 0; k < 2; ++k) \
;         acc[ai][bj][m][n] = __builtin_amdgcn_mfma_f32_16x16x32_bf16(Bt[n][k], At[m][k], acc[ai][bj][m][n], 0, 0, 0); __builtin_amdgcn_s_setprio(0); } while (0)
; #define PG8_WAIT_V(n) asm volatile("s_waitcnt vmcnt(" #n ")" ::: "memory")
; #define PG8_WAIT_L(n) asm volatile("s_waitcnt lgkmcnt(" #n ")" ::: "memory")
; #define PG8_BAR __builtin_amdgcn_s_barrier()
; #define PG8_SCHED __builtin_amdgcn_sched_barrier(0)
; template <class Epi, class Sched, bool ALIGN_EPI = false, bool SP2 = false, bool KSEG = false>
; __device__ __forceinline__ void gemm_phase(PG8_LAS unsigned char* lds, const Gemm g, const Sched& S, const Epi& E) {
;     ...
;         for (int t = 0; t < nt; t += 2) {
;             const bool last = (t == nt - 2);
;             const char* a1 = cA + (size_t)(t + 1) * kstep;
;             const char* a2 = last ? nA : cA + (size_t)(t + 2) * kstep; const char* b2 = last ? nB : cB + (size_t)(t + 2) * kstep;
;             const char* a3 = a2 + kstep; const char* b3 = b2 + kstep;
;     ...
;             PG8_LDA(At, 1, 1); PG8_STAGE(PG8_SB(1, 0), b3, voffB); PG8_STAGE(PG8_SB(1, 1), b3 + hstep, voffB); PG8_STAGE(PG8_SA(1, 0), a3, voffA);
;             PG8_WAIT_V(8); PG8_WAIT_L(0); PG8_BAR; PG8_MMA(1, 0, At, B0); PG8_MMA(1, 1, At, B1); PG8_BAR; PG8_SCHED;
	s_add_i32 s33, s33, s53
	v_lshl_add_u64 v[232:233], v[232:233], 0, s[12:13]
	s_mov_b32 m0, s33
	ds_read_b128 v[200:203], v164 offset:49152
	ds_read_b128 v[204:207], v164 offset:50176
	ds_read_b128 v[208:211], v164 offset:51200
	ds_read_b128 v[212:215], v164 offset:52224
	ds_read_b128 v[216:219], v164 offset:53248
	ds_read_b128 v[220:223], v164 offset:54272
	ds_read_b128 v[224:227], v164 offset:55296
	ds_read_b128 v[228:231], v164 offset:56320
	global_load_lds_dwordx4 v[232:233], off
	s_add_i32 m0, s33, 0x2000
	s_add_u32 s42, s42, 0x80080
	v_lshl_add_u64 v[232:233], v[234:235], 0, s[12:13]
	s_addc_u32 s43, s43, 0
	s_add_i32 s33, s80, s53
	global_load_lds_dwordx4 v[232:233], off
	s_mov_b32 m0, s33
	v_lshl_add_u64 v[232:233], s[42:43], 0, v[134:135]
	global_load_lds_dwordx4 v[232:233], off
	s_add_i32 m0, s33, 0x2000
	v_lshl_add_u64 v[232:233], s[42:43], 0, v[138:139]
	global_load_lds_dwordx4 v[232:233], off
	s_waitcnt vmcnt(6) lgkmcnt(0)
	s_barrier
	s_setprio 1
	v_mfma_f32_16x16x32_bf16 v[62:65], v[154:157], v[200:203], v[62:65]
	v_mfma_f32_16x16x32_bf16 v[58:61], v[176:179], v[200:203], v[58:61]
	v_mfma_f32_16x16x32_bf16 v[46:49], v[154:157], v[208:211], v[46:49]
	v_mfma_f32_16x16x32_bf16 v[42:45], v[176:179], v[208:211], v[42:45]
	v_mfma_f32_16x16x32_bf16 v[30:33], v[154:157], v[216:219], v[30:33]
	v_mfma_f32_16x16x32_bf16 v[26:29], v[176:179], v[216:219], v[26:29]
	v_mfma_f32_16x16x32_bf16 v[14:17], v[154:157], v[224:227], v[14:17]
	v_mfma_f32_16x16x32_bf16 v[10:13], v[176:179], v[224:227], v[10:13]
	v_mfma_f32_16x16x32_bf16 v[62:65], v[172:175], v[204:207], v[62:65]
	v_mfma_f32_16x16x32_bf16 v[58:61], v[180:183], v[204:207], v[58:61]
	v_mfma_f32_16x16x32_bf16 v[46:49], v[172:175], v[212:215], v[46:49]
	v_mfma_f32_16x16x32_bf16 v[42:45], v[180:183], v[212:215], v[42:45]
	v_mfma_f32_16x16x32_bf16 v[30:33], v[172:175], v[220:223], v[30:33]
	v_mfma_f32_16x16x32_bf16 v[26:29], v[180:183], v[220:223], v[26:29]
	v_mfma_f32_16x16x32_bf16 v[14:17], v[172:175], v[228:231], v[14:17]
	v_mfma_f32_16x16x32_bf16 v[10:13], v[180:183], v[228:231], v[10:13]
	s_setprio 0
	s_setprio 1
	v_mfma_f32_16x16x32_bf16 v[54:57], v[184:187], v[200:203], v[54:57]
	s_add_i32 s79, s79, 2
	v_mfma_f32_16x16x32_bf16 v[50:53], v[192:195], v[200:203], v[50:53]
	s_add_u32 s40, s40, 0x100
	v_mfma_f32_16x16x32_bf16 v[38:41], v[184:187], v[208:211], v[38:41]
	s_addc_u32 s41, s41, 0
	v_mfma_f32_16x16x32_bf16 v[34:37], v[192:195], v[208:211], v[34:37]
	s_add_u32 s67, s67, 0x100
	v_mfma_f32_16x16x32_bf16 v[22:25], v[184:187], v[216:219], v[22:25]
	s_addc_u32 s78, s78, 0
	v_mfma_f32_16x16x32_bf16 v[18:21], v[192:195], v[216:219], v[18:21]
	s_add_u32 s33, s40, 0xfff80080
	v_mfma_f32_16x16x32_bf16 v[6:9], v[184:187], v[224:227], v[6:9]
	s_addc_u32 s42, s41, -1
	v_mfma_f32_16x16x32_bf16 v[2:5], v[192:195], v[224:227], v[2:5]
	s_cmp_eq_u32 s79, 28
	v_mfma_f32_16x16x32_bf16 v[54:57], v[188:191], v[204:207], v[54:57]
	s_cselect_b32 s45, s29, s42
	v_mfma_f32_16x16x32_bf16 v[50:53], v[196:199], v[204:207], v[50:53]
	s_cselect_b32 s44, s65, s33
	v_mfma_f32_16x16x32_bf16 v[38:41], v[188:191], v[212:215], v[38:41]
	s_cselect_b32 s43, s27, s78
	v_mfma_f32_16x16x32_bf16 v[34:37], v[196:199], v[212:215], v[34:37]
	s_cselect_b32 s42, s66, s67
	v_mfma_f32_16x16x32_bf16 v[22:25], v[188:191], v[220:223], v[22:25]
	s_add_u32 s98, s40, 0xfff80000
	v_mfma_f32_16x16x32_bf16 v[18:21], v[196:199], v[220:223], v[18:21]
	s_addc_u32 s99, s41, -1
	v_mfma_f32_16x16x32_bf16 v[6:9], v[188:191], v[228:231], v[6:9]
	s_cmp_lt_u32 s79, 30
	v_mfma_f32_16x16x32_bf16 v[2:5], v[196:199], v[228:231], v[2:5]
	s_setprio 0
	s_barrier
	s_cbranch_scc1 .LBB0_581
	s_andn2_b64 vcc, exec, s[24:25]
	s_cbranch_vccnz .LBB0_584
	s_barrier

; template <class Epi, class Sched, bool ALIGN_EPI = false, bool SP2 = false, bool KSEG = false>
; __device__ __forceinline__ void gemm_phase(PG8_LAS unsigned char* lds, const Gemm g, const Sched& S, const Epi& E) {
;     ...
;         for (int t = 0; t < nt; t += 2) {
;             const bool last = (t == nt - 2);
;             const char* a1 = cA + (size_t)(t + 1) * kstep;
;             const char* a2 = last ? nA : cA + (size_t)(t + 2) * kstep; const char* b2 = last ? nB : cB + (size_t)(t + 2) * kstep;
;             const char* a3 = a2 + kstep; const char* b3 = b2 + kstep;
;     ...
; #pragma unroll
;         for (int a = 0; a < 2; ++a)
; #pragma unroll
;             for (int b = 0; b < 2; ++b)
; #pragma unroll
;                 for (int m = 0; m < 4; ++m)
; #pragma unroll
;                     for (int n = 0; n < 2; ++n) acc[a][b][m][n] = (f32x4){0.f, 0.f, 0.f, 0.f};
;         cur = nxt; cA = nA; cB = nB; ++ui;
.LBB0_620:
	s_add_u32 s24, s24, 0x160080
	s_addc_u32 s25, s25, 0
	s_add_u32 s48, s26, 0x100
	v_mov_b32_e32 v2, 0
	s_addc_u32 s49, s27, 0
	s_mov_b32 s50, -2
	v_mov_b32_e32 v3, v2
	v_mov_b32_e32 v4, v2
	v_mov_b32_e32 v5, v2
	v_mov_b32_e32 v6, v2
	v_mov_b32_e32 v7, v2
	v_mov_b32_e32 v8, v2
	v_mov_b32_e32 v9, v2
	v_mov_b32_e32 v18, v2
	v_mov_b32_e32 v19, v2
	v_mov_b32_e32 v20, v2
	v_mov_b32_e32 v21, v2
	v_mov_b32_e32 v22, v2
	v_mov_b32_e32 v23, v2
	v_mov_b32_e32 v24, v2
	v_mov_b32_e32 v25, v2
	v_mov_b32_e32 v34, v2
	v_mov_b32_e32 v35, v2
	v_mov_b32_e32 v36, v2
	v_mov_b32_e32 v37, v2
	v_mov_b32_e32 v38, v2
	s_waitcnt lgkmcnt(0)
	v_mov_b32_e32 v39, v2
	v_mov_b32_e32 v40, v2
	v_mov_b32_e32 v41, v2
	v_mov_b32_e32 v50, v2
	v_mov_b32_e32 v51, v2
	v_mov_b32_e32 v52, v2
	v_mov_b32_e32 v53, v2
	v_mov_b32_e32 v54, v2
	v_mov_b32_e32 v55, v2
	v_mov_b32_e32 v56, v2
	v_mov_b32_e32 v57, v2
	v_mov_b32_e32 v10, v2
	v_mov_b32_e32 v11, v2
	v_mov_b32_e32 v12, v2
	v_mov_b32_e32 v13, v2
	v_mov_b32_e32 v14, v2
	v_mov_b32_e32 v15, v2
	v_mov_b32_e32 v16, v2
	v_mov_b32_e32 v17, v2
	v_mov_b32_e32 v26, v2
	v_mov_b32_e32 v27, v2
	v_mov_b32_e32 v28, v2
	v_mov_b32_e32 v29, v2
	v_mov_b32_e32 v30, v2
	v_mov_b32_e32 v31, v2
	v_mov_b32_e32 v32, v2
	v_mov_b32_e32 v33, v2
	v_mov_b32_e32 v42, v2
	v_mov_b32_e32 v43, v2
	v_mov_b32_e32 v44, v2
	v_mov_b32_e32 v45, v2
	v_mov_b32_e32 v46, v2
	v_mov_b32_e32 v47, v2
	v_mov_b32_e32 v48, v2
	v_mov_b32_e32 v49, v2
	v_mov_b32_e32 v58, v2
	v_mov_b32_e32 v59, v2
	v_mov_b32_e32 v60, v2
	v_mov_b32_e32 v61, v2
	v_mov_b32_e32 v62, v2
	v_mov_b32_e32 v63, v2
	v_mov_b32_e32 v64, v2
	v_mov_b32_e32 v65, v2
	v_mov_b32_e32 v66, v2
	v_mov_b32_e32 v67, v2
	v_mov_b32_e32 v68, v2
	v_mov_b32_e32 v69, v2
	v_mov_b32_e32 v70, v2
	v_mov_b32_e32 v71, v2
	v_mov_b32_e32 v72, v2
	v_mov_b32_e32 v73, v2
	v_mov_b32_e32 v82, v2
	v_mov_b32_e32 v83, v2
	v_mov_b32_e32 v84, v2
	v_mov_b32_e32 v85, v2
	v_mov_b32_e32 v86, v2
	v_mov_b32_e32 v87, v2
	v_mov_b32_e32 v88, v2
	v_mov_b32_e32 v89, v2
	v_mov_b32_e32 v98, v2
	v_mov_b32_e32 v99, v2
	v_mov_b32_e32 v100, v2
	v_mov_b32_e32 v101, v2
	v_mov_b32_e32 v102, v2
	v_mov_b32_e32 v103, v2
	v_mov_b32_e32 v104, v2
	v_mov_b32_e32 v105, v2
	v_mov_b32_e32 v114, v2
	v_mov_b32_e32 v115, v2
	v_mov_b32_e32 v116, v2
	v_mov_b32_e32 v117, v2
	v_mov_b32_e32 v118, v2
	v_mov_b32_e32 v119, v2
	v_mov_b32_e32 v120, v2
	v_mov_b32_e32 v121, v2
	v_mov_b32_e32 v74, v2
	v_mov_b32_e32 v75, v2
	v_mov_b32_e32 v76, v2
	v_mov_b32_e32 v77, v2
	v_mov_b32_e32 v78, v2
	v_mov_b32_e32 v79, v2
	v_mov_b32_e32 v80, v2
	v_mov_b32_e32 v81, v2
	v_mov_b32_e32 v90, v2
	v_mov_b32_e32 v91, v2
	v_mov_b32_e32 v92, v2
	v_mov_b32_e32 v93, v2
	v_mov_b32_e32 v94, v2
	v_mov_b32_e32 v95, v2
	v_mov_b32_e32 v96, v2
	v_mov_b32_e32 v97, v2
	v_mov_b32_e32 v106, v2
	v_mov_b32_e32 v107, v2
	v_mov_b32_e32 v108, v2
	v_mov_b32_e32 v109, v2
	v_mov_b32_e32 v110, v2
	v_mov_b32_e32 v111, v2
	v_mov_b32_e32 v112, v2
	v_mov_b32_e32 v113, v2
	v_mov_b32_e32 v122, v2
	v_mov_b32_e32 v123, v2
	v_mov_b32_e32 v124, v2
	v_mov_b32_e32 v125, v2
	v_mov_b32_e32 v126, v2
	v_mov_b32_e32 v127, v2
	v_mov_b32_e32 v128, v2
	v_mov_b32_e32 v129, v2
	s_add_u32 s26, s24, 0xffea0080
	s_addc_u32 s27, s25, -1
	s_cmpk_eq_i32 s50, 0x54
	s_cselect_b32 s29, s21, s27
	s_cselect_b32 s28, s20, s26
	s_cselect_b32 s27, s9, s49
	s_cselect_b32 s26, s8, s48
	s_add_u32 s98, s24, 0xffea0000
	s_addc_u32 s99, s25, -1
.LBB0_621:
	ds_read_b128 v[146:149], v1
	ds_read_b128 v[156:159], v1 offset:1024
	ds_read_b128 v[160:163], v1 offset:2048
	ds_read_b128 v[164:167], v1 offset:3072
	ds_read_b128 v[168:171], v153
	ds_read_b128 v[172:175], v153 offset:1024
	ds_read_b128 v[176:179], v153 offset:2048
	ds_read_b128 v[180:183], v153 offset:3072
	s_mov_b32 m0, s40
	v_lshl_add_u64 v[216:217], s[98:99], 0, v[140:141]
	global_load_lds_dwordx4 v[216:217], off
	s_mov_b32 m0, s41
	v_lshl_add_u64 v[216:217], s[98:99], 0, v[142:143]
	global_load_lds_dwordx4 v[216:217], off
	v_lshl_add_u64 v[216:217], s[24:25], 0, v[132:133]
	s_add_i32 m0, s31, 0xc000
	ds_read_b128 v[184:187], v154
	ds_read_b128 v[188:191], v154 offset:1024
	ds_read_b128 v[192:195], v154 offset:2048
	ds_read_b128 v[196:199], v154 offset:3072
	ds_read_b128 v[200:203], v154 offset:4096
	ds_read_b128 v[204:207], v154 offset:5120
	ds_read_b128 v[208:211], v154 offset:6144
	ds_read_b128 v[212:215], v154 offset:7168
	global_load_lds_dwordx4 v[216:217], off
	s_add_i32 m0, s31, 0xe000
	v_lshl_add_u64 v[216:217], s[24:25], 0, v[134:135]
	global_load_lds_dwordx4 v[216:217], off
	s_waitcnt vmcnt(8) lgkmcnt(0)
	s_barrier
; #define PG8_STAGE(bufoff, gbase, voff) do { _Pragma("unroll") for (int _i = 0; _i < 2; ++_i) \
;         __builtin_amdgcn_global_load_lds((const unsigned*)((const char*)(gbase) + (voff)[_i]), (PG8_LAS unsigned*)(lds + (bufoff) + ldsw + _i * 8192), 16, 0, 0); } while (0)
; #define PG8_LDA(dst, b, h) do { _Pragma("unroll") for (int m = 0; m < 4; ++m) _Pragma("unroll") for (int k = 0; k < 2; ++k) dst[m][k] = *(const PG8_LAS bf16x8*)(lds + PG8_SA(b, h) + aoff + m * 2048 + k * 1024); } while (0)
; #define PG8_LDB(dst, b, h) do { _Pragma("unroll") for (int n = 0; n < 2; ++n) _Pragma("unroll") for (int k = 0; k < 2; ++k) dst[n][k] = *(const PG8_LAS bf16x8*)(lds + PG8_SB(b, h) + boff + n * 2048 + k * 1024); } while (0)
; #define PG8_MMA(ai, bj, At, Bt) do { __builtin_amdgcn_s_setprio(1); _Pragma("unroll") for (int m = 0; m < 4; ++m) _Pragma("unroll") for (int n = 0; n < 2; ++n) _Pragma("unroll") for (int k = 0; k < 2; ++k) \
;         acc[ai][bj][m][n] = __builtin_amdgcn_mfma_f32_16x16x32_bf16(Bt[n][k], At[m][k], acc[ai][bj][m][n], 0, 0, 0); __builtin_amdgcn_s_setprio(0); } while (0)
; #define PG8_WAIT_V(n) asm volatile("s_waitcnt vmcnt(" #n ")" ::: "memory")
; #define PG8_WAIT_L(n) asm volatile("s_waitcnt lgkmcnt(" #n ")" ::: "memory")
; #define PG8_BAR __builtin_amdgcn_s_barrier()
; #define PG8_SCHED __builtin_amdgcn_sched_barrier(0)
; template <class Epi, class Sched, bool ALIGN_EPI = false, bool SP2 = false, bool KSEG = false>
; __device__ __forceinline__ void gemm_phase(PG8_LAS unsigned char* lds, const Gemm g, const Sched& S, const Epi& E) {
;     ...
;             PG8_LDB(B0, 0, 0); PG8_LDB(B1, 0, 1); PG8_SCHED; PG8_LDA(At, 0, 0); PG8_STAGE(PG8_SA(1, 1), a1 + hstep, voffA);
;             PG8_WAIT_V(8); PG8_WAIT_L(0); PG8_BAR; PG8_MMA(0, 0, At, B0); PG8_MMA(0, 1, At, B1); PG8_BAR; PG8_SCHED;
;             PG8_LDA(At, 0, 1); PG8_STAGE(PG8_SB(0, 0), b2, voffB); PG8_STAGE(PG8_SB(0, 1), b2 + hstep, voffB); PG8_STAGE(PG8_SA(0, 0), a2, voffA);
;             PG8_WAIT_V(8); PG8_WAIT_L(0); PG8_BAR; PG8_MMA(1, 0, At, B0); PG8_MMA(1, 1, At, B1); PG8_BAR; PG8_SCHED;
	s_setprio 1
	v_mfma_f32_16x16x32_bf16 v[126:129], v[146:149], v[184:187], v[126:129]
	v_mfma_f32_16x16x32_bf16 v[122:125], v[160:163], v[184:187], v[122:125]
	v_mfma_f32_16x16x32_bf16 v[110:113], v[146:149], v[192:195], v[110:113]
	v_mfma_f32_16x16x32_bf16 v[106:109], v[160:163], v[192:195], v[106:109]
	v_mfma_f32_16x16x32_bf16 v[94:97], v[146:149], v[200:203], v[94:97]
	v_mfma_f32_16x16x32_bf16 v[90:93], v[160:163], v[200:203], v[90:93]
	v_mfma_f32_16x16x32_bf16 v[78:81], v[146:149], v[208:211], v[78:81]
	v_mfma_f32_16x16x32_bf16 v[74:77], v[160:163], v[208:211], v[74:77]
	v_mfma_f32_16x16x32_bf16 v[126:129], v[156:159], v[188:191], v[126:129]
	v_mfma_f32_16x16x32_bf16 v[122:125], v[164:167], v[188:191], v[122:125]
	v_mfma_f32_16x16x32_bf16 v[110:113], v[156:159], v[196:199], v[110:113]
	v_mfma_f32_16x16x32_bf16 v[106:109], v[164:167], v[196:199], v[106:109]
	v_mfma_f32_16x16x32_bf16 v[94:97], v[156:159], v[204:207], v[94:97]
	v_mfma_f32_16x16x32_bf16 v[90:93], v[164:167], v[204:207], v[90:93]
	v_mfma_f32_16x16x32_bf16 v[78:81], v[156:159], v[212:215], v[78:81]
	v_mfma_f32_16x16x32_bf16 v[74:77], v[164:167], v[212:215], v[74:77]
	s_setprio 0
	s_setprio 1
	v_mfma_f32_16x16x32_bf16 v[118:121], v[168:171], v[184:187], v[118:121]
	v_mfma_f32_16x16x32_bf16 v[114:117], v[176:179], v[184:187], v[114:117]
	v_mfma_f32_16x16x32_bf16 v[102:105], v[168:171], v[192:195], v[102:105]
	v_mfma_f32_16x16x32_bf16 v[98:101], v[176:179], v[192:195], v[98:101]
	v_mfma_f32_16x16x32_bf16 v[86:89], v[168:171], v[200:203], v[86:89]
	v_mfma_f32_16x16x32_bf16 v[82:85], v[176:179], v[200:203], v[82:85]
	v_mfma_f32_16x16x32_bf16 v[70:73], v[168:171], v[208:211], v[70:73]
	v_mfma_f32_16x16x32_bf16 v[66:69], v[176:179], v[208:211], v[66:69]
	v_mfma_f32_16x16x32_bf16 v[118:121], v[172:175], v[188:191], v[118:121]
	v_mfma_f32_16x16x32_bf16 v[114:117], v[180:183], v[188:191], v[114:117]
	v_mfma_f32_16x16x32_bf16 v[102:105], v[172:175], v[196:199], v[102:105]
	v_mfma_f32_16x16x32_bf16 v[98:101], v[180:183], v[196:199], v[98:101]
	v_mfma_f32_16x16x32_bf16 v[86:89], v[172:175], v[204:207], v[86:89]
	v_mfma_f32_16x16x32_bf16 v[82:85], v[180:183], v[204:207], v[82:85]
	v_mfma_f32_16x16x32_bf16 v[70:73], v[172:175], v[212:215], v[70:73]
	v_mfma_f32_16x16x32_bf16 v[66:69], v[180:183], v[212:215], v[66:69]
	s_setprio 0
	s_barrier
	s_add_i32 s33, s42, s30
	v_lshl_add_u64 v[216:217], s[26:27], 0, v[130:131]
	s_mov_b32 m0, s33
	ds_read_b128 v[184:187], v154 offset:16384
	ds_read_b128 v[188:191], v154 offset:17408
	ds_read_b128 v[192:195], v154 offset:18432
	ds_read_b128 v[196:199], v154 offset:19456
	ds_read_b128 v[200:203], v154 offset:20480
	ds_read_b128 v[204:207], v154 offset:21504
	ds_read_b128 v[208:211], v154 offset:22528
	ds_read_b128 v[212:215], v154 offset:23552
	global_load_lds_dwordx4 v[216:217], off
	s_add_i32 m0, s33, 0x2000
	s_add_u32 s54, s26, 0x160000
	v_lshl_add_u64 v[218:219], s[26:27], 0, v[144:145]
	s_addc_u32 s55, s27, 0
	s_add_i32 s33, s43, s30
	global_load_lds_dwordx4 v[218:219], off
	s_mov_b32 m0, s33
	v_lshl_add_u64 v[220:221], s[54:55], 0, v[130:131]
	global_load_lds_dwordx4 v[220:221], off
	s_add_i32 m0, s33, 0x2000
	v_lshl_add_u64 v[220:221], s[54:55], 0, v[144:145]
	global_load_lds_dwordx4 v[220:221], off
	s_waitcnt vmcnt(6) lgkmcnt(0)
	s_barrier
	s_setprio 1
	v_mfma_f32_16x16x32_bf16 v[62:65], v[146:149], v[184:187], v[62:65]
	v_mfma_f32_16x16x32_bf16 v[58:61], v[160:163], v[184:187], v[58:61]
	v_mfma_f32_16x16x32_bf16 v[46:49], v[146:149], v[192:195], v[46:49]
	v_mfma_f32_16x16x32_bf16 v[42:45], v[160:163], v[192:195], v[42:45]
	v_mfma_f32_16x16x32_bf16 v[30:33], v[146:149], v[200:203], v[30:33]
	v_mfma_f32_16x16x32_bf16 v[26:29], v[160:163], v[200:203], v[26:29]
	v_mfma_f32_16x16x32_bf16 v[14:17], v[146:149], v[208:211], v[14:17]
	v_mfma_f32_16x16x32_bf16 v[10:13], v[160:163], v[208:211], v[10:13]
	v_mfma_f32_16x16x32_bf16 v[62:65], v[156:159], v[188:191], v[62:65]
	v_mfma_f32_16x16x32_bf16 v[58:61], v[164:167], v[188:191], v[58:61]
	v_mfma_f32_16x16x32_bf16 v[46:49], v[156:159], v[196:199], v[46:49]
	v_mfma_f32_16x16x32_bf16 v[42:45], v[164:167], v[196:199], v[42:45]
	v_mfma_f32_16x16x32_bf16 v[30:33], v[156:159], v[204:207], v[30:33]
	v_mfma_f32_16x16x32_bf16 v[26:29], v[164:167], v[204:207], v[26:29]
	v_mfma_f32_16x16x32_bf16 v[14:17], v[156:159], v[212:215], v[14:17]
	v_mfma_f32_16x16x32_bf16 v[10:13], v[164:167], v[212:215], v[10:13]
	s_setprio 0
	s_setprio 1
	v_mfma_f32_16x16x32_bf16 v[54:57], v[168:171], v[184:187], v[54:57]
	v_mfma_f32_16x16x32_bf16 v[50:53], v[176:179], v[184:187], v[50:53]
	v_mfma_f32_16x16x32_bf16 v[38:41], v[168:171], v[192:195], v[38:41]
	v_mfma_f32_16x16x32_bf16 v[34:37], v[176:179], v[192:195], v[34:37]
	v_mfma_f32_16x16x32_bf16 v[22:25], v[168:171], v[200:203], v[22:25]
	v_mfma_f32_16x16x32_bf16 v[18:21], v[176:179], v[200:203], v[18:21]
	v_mfma_f32_16x16x32_bf16 v[6:9], v[168:171], v[208:211], v[6:9]
	v_mfma_f32_16x16x32_bf16 v[2:5], v[176:179], v[208:211], v[2:5]
	v_mfma_f32_16x16x32_bf16 v[54:57], v[172:175], v[188:191], v[54:57]
	v_mfma_f32_16x16x32_bf16 v[50:53], v[180:183], v[188:191], v[50:53]
	v_mfma_f32_16x16x32_bf16 v[38:41], v[172:175], v[196:199], v[38:41]
	v_mfma_f32_16x16x32_bf16 v[34:37], v[180:183], v[196:199], v[34:37]
	v_mfma_f32_16x16x32_bf16 v[22:25], v[172:175], v[204:207], v[22:25]
	v_mfma_f32_16x16x32_bf16 v[18:21], v[180:183], v[204:207], v[18:21]
	v_mfma_f32_16x16x32_bf16 v[6:9], v[172:175], v[212:215], v[6:9]
	v_mfma_f32_16x16x32_bf16 v[2:5], v[180:183], v[212:215], v[2:5]
	s_setprio 0
	s_barrier
; #define PG8_STAGE(bufoff, gbase, voff) do { _Pragma("unroll") for (int _i = 0; _i < 2; ++_i) \
;         __builtin_amdgcn_global_load_lds((const unsigned*)((const char*)(gbase) + (voff)[_i]), (PG8_LAS unsigned*)(lds + (bufoff) + ldsw + _i * 8192), 16, 0, 0); } while (0)
; #define PG8_LDA(dst, b, h) do { _Pragma("unroll") for (int m = 0; m < 4; ++m) _Pragma("unroll") for (int k = 0; k < 2; ++k) dst[m][k] = *(const PG8_LAS bf16x8*)(lds + PG8_SA(b, h) + aoff + m * 2048 + k * 1024); } while (0)
; #define PG8_LDB(dst, b, h) do { _Pragma("unroll") for (int n = 0; n < 2; ++n) _Pragma("unroll") for (int k = 0; k < 2; ++k) dst[n][k] = *(const PG8_LAS bf16x8*)(lds + PG8_SB(b, h) + boff + n * 2048 + k * 1024); } while (0)
; #define PG8_MMA(ai, bj, At, Bt) do { __builtin_amdgcn_s_setprio(1); _Pragma("unroll") for (int m = 0; m < 4; ++m) _Pragma("unroll") for (int n = 0; n < 2; ++n) _Pragma("unroll") for (int k = 0; k < 2; ++k) \
;         acc[ai][bj][m][n] = __builtin_amdgcn_mfma_f32_16x16x32_bf16(Bt[n][k], At[m][k], acc[ai][bj][m][n], 0, 0, 0); __builtin_amdgcn_s_setprio(0); } while (0)
; #define PG8_WAIT_V(n) asm volatile("s_waitcnt vmcnt(" #n ")" ::: "memory")
; #define PG8_WAIT_L(n) asm volatile("s_waitcnt lgkmcnt(" #n ")" ::: "memory")
; #define PG8_BAR __builtin_amdgcn_s_barrier()
; #define PG8_SCHED __builtin_amdgcn_sched_barrier(0)
; template <class Epi, class Sched, bool ALIGN_EPI = false, bool SP2 = false, bool KSEG = false>
; __device__ __forceinline__ void gemm_phase(PG8_LAS unsigned char* lds, const Gemm g, const Sched& S, const Epi& E) {
;     ...
;             PG8_LDB(B0, 1, 0); PG8_LDB(B1, 1, 1); PG8_SCHED; PG8_LDA(At, 1, 0); PG8_STAGE(PG8_SA(0, 1), a2 + hstep, voffA);
;             PG8_WAIT_V(8); PG8_WAIT_L(0); PG8_BAR; PG8_MMA(0, 0, At, B0); PG8_MMA(0, 1, At, B1); PG8_BAR; PG8_SCHED;
	s_add_i32 s33, 0, 0x18000
	v_add_u32_e32 v155, s33, v150
	s_add_i32 s53, 0, 0x1c000
	ds_read_b128 v[146:149], v155
	ds_read_b128 v[156:159], v155 offset:1024
	ds_read_b128 v[160:163], v155 offset:2048
	ds_read_b128 v[164:167], v155 offset:3072
	v_add_u32_e32 v155, s53, v150
	ds_read_b128 v[168:171], v155
	ds_read_b128 v[172:175], v155 offset:1024
	ds_read_b128 v[176:179], v155 offset:2048
	ds_read_b128 v[180:183], v155 offset:3072
	s_mov_b32 m0, s31
	v_lshl_add_u64 v[224:225], s[28:29], 0, v[140:141]
	global_load_lds_dwordx4 v[224:225], off
	s_mov_b32 m0, s36
	v_lshl_add_u64 v[224:225], s[28:29], 0, v[142:143]
	global_load_lds_dwordx4 v[224:225], off
	s_add_u32 s28, s28, 0x160000
	s_addc_u32 s29, s29, 0
	s_mov_b32 m0, s37
	v_lshl_add_u64 v[224:225], s[28:29], 0, v[140:141]
	ds_read_b128 v[184:187], v154 offset:32768
	ds_read_b128 v[188:191], v154 offset:33792
	ds_read_b128 v[192:195], v154 offset:34816
	ds_read_b128 v[196:199], v154 offset:35840
	ds_read_b128 v[200:203], v154 offset:36864
	ds_read_b128 v[204:207], v154 offset:37888
	ds_read_b128 v[208:211], v154 offset:38912
	ds_read_b128 v[212:215], v154 offset:39936
	global_load_lds_dwordx4 v[224:225], off
	s_mov_b32 m0, s38
	v_lshl_add_u64 v[224:225], s[28:29], 0, v[142:143]
	global_load_lds_dwordx4 v[224:225], off
	s_waitcnt vmcnt(8) lgkmcnt(0)
	s_barrier
	s_setprio 1
	v_mfma_f32_16x16x32_bf16 v[126:129], v[146:149], v[184:187], v[126:129]
	v_mfma_f32_16x16x32_bf16 v[122:125], v[160:163], v[184:187], v[122:125]
	v_mfma_f32_16x16x32_bf16 v[110:113], v[146:149], v[192:195], v[110:113]
	v_mfma_f32_16x16x32_bf16 v[106:109], v[160:163], v[192:195], v[106:109]
	v_mfma_f32_16x16x32_bf16 v[94:97], v[146:149], v[200:203], v[94:97]
	v_mfma_f32_16x16x32_bf16 v[90:93], v[160:163], v[200:203], v[90:93]
	v_mfma_f32_16x16x32_bf16 v[78:81], v[146:149], v[208:211], v[78:81]
	v_mfma_f32_16x16x32_bf16 v[74:77], v[160:163], v[208:211], v[74:77]
	v_mfma_f32_16x16x32_bf16 v[126:129], v[156:159], v[188:191], v[126:129]
	v_mfma_f32_16x16x32_bf16 v[122:125], v[164:167], v[188:191], v[122:125]
	v_mfma_f32_16x16x32_bf16 v[110:113], v[156:159], v[196:199], v[110:113]
	v_mfma_f32_16x16x32_bf16 v[106:109], v[164:167], v[196:199], v[106:109]
	v_mfma_f32_16x16x32_bf16 v[94:97], v[156:159], v[204:207], v[94:97]
	v_mfma_f32_16x16x32_bf16 v[90:93], v[164:167], v[204:207], v[90:93]
	v_mfma_f32_16x16x32_bf16 v[78:81], v[156:159], v[212:215], v[78:81]
	v_mfma_f32_16x16x32_bf16 v[74:77], v[164:167], v[212:215], v[74:77]
	s_setprio 0
	s_setprio 1
	v_mfma_f32_16x16x32_bf16 v[118:121], v[168:171], v[184:187], v[118:121]
	v_mfma_f32_16x16x32_bf16 v[114:117], v[176:179], v[184:187], v[114:117]
	v_mfma_f32_16x16x32_bf16 v[102:105], v[168:171], v[192:195], v[102:105]
	v_mfma_f32_16x16x32_bf16 v[98:101], v[176:179], v[192:195], v[98:101]
	v_mfma_f32_16x16x32_bf16 v[86:89], v[168:171], v[200:203], v[86:89]
	v_mfma_f32_16x16x32_bf16 v[82:85], v[176:179], v[200:203], v[82:85]
	v_mfma_f32_16x16x32_bf16 v[70:73], v[168:171], v[208:211], v[70:73]
	v_mfma_f32_16x16x32_bf16 v[66:69], v[176:179], v[208:211], v[66:69]
	v_mfma_f32_16x16x32_bf16 v[118:121], v[172:175], v[188:191], v[118:121]
	v_mfma_f32_16x16x32_bf16 v[114:117], v[180:183], v[188:191], v[114:117]
	v_mfma_f32_16x16x32_bf16 v[102:105], v[172:175], v[196:199], v[102:105]
	v_mfma_f32_16x16x32_bf16 v[98:101], v[180:183], v[196:199], v[98:101]
	v_mfma_f32_16x16x32_bf16 v[86:89], v[172:175], v[204:207], v[86:89]
	v_mfma_f32_16x16x32_bf16 v[82:85], v[180:183], v[204:207], v[82:85]
	v_mfma_f32_16x16x32_bf16 v[70:73], v[172:175], v[212:215], v[70:73]
	v_mfma_f32_16x16x32_bf16 v[66:69], v[180:183], v[212:215], v[66:69]
	s_setprio 0
	s_barrier
; #define PG8_STAGE(bufoff, gbase, voff) do { _Pragma("unroll") for (int _i = 0; _i < 2; ++_i) \
;         __builtin_amdgcn_global_load_lds((const unsigned*)((const char*)(gbase) + (voff)[_i]), (PG8_LAS unsigned*)(lds + (bufoff) + ldsw + _i * 8192), 16, 0, 0); } while (0)
; #define PG8_LDA(dst, b, h) do { _Pragma("unroll") for (int m = 0; m < 4; ++m) _Pragma("unroll") for (int k = 0; k < 2; ++k) dst[m][k] = *(const PG8_LAS bf16x8*)(lds + PG8_SA(b, h) + aoff + m * 2048 + k * 1024); } while (0)
; #define PG8_MMA(ai, bj, At, Bt) do { __builtin_amdgcn_s_setprio(1); _Pragma("unroll") for (int m = 0; m < 4; ++m) _Pragma("unroll") for (int n = 0; n < 2; ++n) _Pragma("unroll") for (int k = 0; k < 2; ++k) \
;         acc[ai][bj][m][n] = __builtin_amdgcn_mfma_f32_16x16x32_bf16(Bt[n][k], At[m][k], acc[ai][bj][m][n], 0, 0, 0); __builtin_amdgcn_s_setprio(0); } while (0)
; #define PG8_WAIT_V(n) asm volatile("s_waitcnt vmcnt(" #n ")" ::: "memory")
; #define PG8_WAIT_L(n) asm volatile("s_waitcnt lgkmcnt(" #n ")" ::: "memory")
; #define PG8_BAR __builtin_amdgcn_s_barrier()
; #define PG8_SCHED __builtin_amdgcn_sched_barrier(0)
; template <class Epi, class Sched, bool ALIGN_EPI = false, bool SP2 = false, bool KSEG = false>
; __device__ __forceinline__ void gemm_phase(PG8_LAS unsigned char* lds, const Gemm g, const Sched& S, const Epi& E) {
;     ...
;         for (int t = 0; t < nt; t += 2) {
;             const bool last = (t == nt - 2);
;             const char* a1 = cA + (size_t)(t + 1) * kstep;
;             const char* a2 = last ? nA : cA + (size_t)(t + 2) * kstep; const char* b2 = last ? nB : cB + (size_t)(t + 2) * kstep;
;             const char* a3 = a2 + kstep; const char* b3 = b2 + kstep;
;     ...
;             PG8_LDA(At, 1, 1); PG8_STAGE(PG8_SB(1, 0), b3, voffB); PG8_STAGE(PG8_SB(1, 1), b3 + hstep, voffB); PG8_STAGE(PG8_SA(1, 0), a3, voffA);
;             PG8_WAIT_V(8); PG8_WAIT_L(0); PG8_BAR; PG8_MMA(1, 0, At, B0); PG8_MMA(1, 1, At, B1); PG8_BAR; PG8_SCHED;
	s_add_i32 s28, s33, s30
	v_lshl_add_u64 v[216:217], v[216:217], 0, s[12:13]
	s_mov_b32 m0, s28
	ds_read_b128 v[184:187], v154 offset:49152
	ds_read_b128 v[188:191], v154 offset:50176
	ds_read_b128 v[192:195], v154 offset:51200
	ds_read_b128 v[196:199], v154 offset:52224
	ds_read_b128 v[200:203], v154 offset:53248
	ds_read_b128 v[204:207], v154 offset:54272
	ds_read_b128 v[208:211], v154 offset:55296
	ds_read_b128 v[212:215], v154 offset:56320
	global_load_lds_dwordx4 v[216:217], off
	s_add_i32 m0, s28, 0x2000
	s_add_u32 s26, s26, 0x160080
	v_lshl_add_u64 v[216:217], v[218:219], 0, s[12:13]
	s_addc_u32 s27, s27, 0
	s_add_i32 s28, s53, s30
	global_load_lds_dwordx4 v[216:217], off
	s_mov_b32 m0, s28
	v_lshl_add_u64 v[216:217], s[26:27], 0, v[130:131]
	global_load_lds_dwordx4 v[216:217], off
	s_add_i32 m0, s28, 0x2000
	v_lshl_add_u64 v[216:217], s[26:27], 0, v[144:145]
	global_load_lds_dwordx4 v[216:217], off
	s_waitcnt vmcnt(6) lgkmcnt(0)
	s_barrier
	s_setprio 1
	v_mfma_f32_16x16x32_bf16 v[62:65], v[146:149], v[184:187], v[62:65]
	v_mfma_f32_16x16x32_bf16 v[58:61], v[160:163], v[184:187], v[58:61]
	v_mfma_f32_16x16x32_bf16 v[46:49], v[146:149], v[192:195], v[46:49]
	v_mfma_f32_16x16x32_bf16 v[42:45], v[160:163], v[192:195], v[42:45]
	v_mfma_f32_16x16x32_bf16 v[30:33], v[146:149], v[200:203], v[30:33]
	v_mfma_f32_16x16x32_bf16 v[26:29], v[160:163], v[200:203], v[26:29]
	v_mfma_f32_16x16x32_bf16 v[14:17], v[146:149], v[208:211], v[14:17]
	v_mfma_f32_16x16x32_bf16 v[10:13], v[160:163], v[208:211], v[10:13]
	v_mfma_f32_16x16x32_bf16 v[62:65], v[156:159], v[188:191], v[62:65]
	v_mfma_f32_16x16x32_bf16 v[58:61], v[164:167], v[188:191], v[58:61]
	v_mfma_f32_16x16x32_bf16 v[46:49], v[156:159], v[196:199], v[46:49]
	v_mfma_f32_16x16x32_bf16 v[42:45], v[164:167], v[196:199], v[42:45]
	v_mfma_f32_16x16x32_bf16 v[30:33], v[156:159], v[204:207], v[30:33]
	v_mfma_f32_16x16x32_bf16 v[26:29], v[164:167], v[204:207], v[26:29]
	v_mfma_f32_16x16x32_bf16 v[14:17], v[156:159], v[212:215], v[14:17]
	v_mfma_f32_16x16x32_bf16 v[10:13], v[164:167], v[212:215], v[10:13]
	s_setprio 0
	s_setprio 1
	v_mfma_f32_16x16x32_bf16 v[54:57], v[168:171], v[184:187], v[54:57]
	s_add_i32 s50, s50, 2
	v_mfma_f32_16x16x32_bf16 v[50:53], v[176:179], v[184:187], v[50:53]
	s_add_u32 s24, s24, 0x100
	v_mfma_f32_16x16x32_bf16 v[38:41], v[168:171], v[192:195], v[38:41]
	s_addc_u32 s25, s25, 0
	v_mfma_f32_16x16x32_bf16 v[34:37], v[176:179], v[192:195], v[34:37]
	s_add_u32 s48, s48, 0x100
	v_mfma_f32_16x16x32_bf16 v[22:25], v[168:171], v[200:203], v[22:25]
	s_addc_u32 s49, s49, 0
	v_mfma_f32_16x16x32_bf16 v[18:21], v[176:179], v[200:203], v[18:21]
	s_add_u32 s26, s24, 0xffea0080
	v_mfma_f32_16x16x32_bf16 v[6:9], v[168:171], v[208:211], v[6:9]
	s_addc_u32 s27, s25, -1
	v_mfma_f32_16x16x32_bf16 v[2:5], v[176:179], v[208:211], v[2:5]
	s_cmpk_eq_i32 s50, 0x54
	v_mfma_f32_16x16x32_bf16 v[54:57], v[172:175], v[188:191], v[54:57]
	s_cselect_b32 s29, s21, s27
	v_mfma_f32_16x16x32_bf16 v[50:53], v[180:183], v[188:191], v[50:53]
	s_cselect_b32 s28, s20, s26
	v_mfma_f32_16x16x32_bf16 v[38:41], v[172:175], v[196:199], v[38:41]
	s_cselect_b32 s27, s9, s49
	v_mfma_f32_16x16x32_bf16 v[34:37], v[180:183], v[196:199], v[34:37]
	s_cselect_b32 s26, s8, s48
	v_mfma_f32_16x16x32_bf16 v[22:25], v[172:175], v[204:207], v[22:25]
	s_add_u32 s98, s24, 0xffea0000
	v_mfma_f32_16x16x32_bf16 v[18:21], v[180:183], v[204:207], v[18:21]
	s_addc_u32 s99, s25, -1
	v_mfma_f32_16x16x32_bf16 v[6:9], v[172:175], v[212:215], v[6:9]
	s_cmpk_lt_u32 s50, 0x56
	v_mfma_f32_16x16x32_bf16 v[2:5], v[180:183], v[212:215], v[2:5]
	s_setprio 0
	s_barrier
	s_cbranch_scc1 .LBB0_621
	s_andn2_b64 vcc, exec, s[18:19]
	s_cbranch_vccnz .LBB0_624
	s_barrier
